# v59 plus the K-loop B-fragment LDS read shift into the phase 4/8 load slots
# speedup vs baseline: 1.0104x; 1.0104x over previous
.LBB0_262:
	s_add_u32 s6, s4, 0xfff80080
	s_addc_u32 s7, s5, -1
	s_cmp_eq_u32 s37, 28
	s_cselect_b32 s9, s10, s7
	s_cselect_b32 s8, s11, s6
	s_cselect_b32 s7, s20, s36
	s_cselect_b32 s6, s34, s35
	v_lshl_add_u64 v[176:177], s[4:5], 0, v[158:159]
	s_add_i32 m0, s44, 0xc000
	ds_read_b128 v[144:147], v182
	ds_read_b128 v[168:171], v182 offset:1024
	ds_read_b128 v[172:175], v182 offset:2048
	ds_read_b128 v[184:187], v182 offset:3072
	ds_read_b128 v[188:191], v182 offset:4096
	ds_read_b128 v[192:195], v182 offset:5120
	ds_read_b128 v[196:199], v182 offset:6144
	ds_read_b128 v[200:203], v182 offset:7168
	global_load_lds_dwordx4 v[176:177], off
	v_lshl_add_u64 v[176:177], s[4:5], 0, v[160:161]
	s_add_i32 m0, s44, 0xe000
	s_nop 0
	global_load_lds_dwordx4 v[176:177], off
	s_waitcnt lgkmcnt(8)
	s_barrier
	s_waitcnt lgkmcnt(0)
	s_waitcnt lgkmcnt(0)
	v_mfma_f32_16x16x32_bf16 v[124:127], v[128:131], v[144:147], v[124:127]
	v_mfma_f32_16x16x32_bf16 v[120:123], v[136:139], v[144:147], v[120:123]
	v_mfma_f32_16x16x32_bf16 v[108:111], v[128:131], v[172:175], v[108:111]
	v_mfma_f32_16x16x32_bf16 v[104:107], v[136:139], v[172:175], v[104:107]
	v_mfma_f32_16x16x32_bf16 v[92:95], v[128:131], v[188:191], v[92:95]
	v_mfma_f32_16x16x32_bf16 v[88:91], v[136:139], v[188:191], v[88:91]
	v_mfma_f32_16x16x32_bf16 v[76:79], v[128:131], v[196:199], v[76:79]
	v_mfma_f32_16x16x32_bf16 v[72:75], v[136:139], v[196:199], v[72:75]
	v_mfma_f32_16x16x32_bf16 v[124:127], v[132:135], v[168:171], v[124:127]
	v_mfma_f32_16x16x32_bf16 v[120:123], v[140:143], v[168:171], v[120:123]
	v_mfma_f32_16x16x32_bf16 v[108:111], v[132:135], v[184:187], v[108:111]
	v_mfma_f32_16x16x32_bf16 v[104:107], v[140:143], v[184:187], v[104:107]
	v_mfma_f32_16x16x32_bf16 v[92:95], v[132:135], v[192:195], v[92:95]
	v_mfma_f32_16x16x32_bf16 v[88:91], v[140:143], v[192:195], v[88:91]
	v_mfma_f32_16x16x32_bf16 v[76:79], v[132:135], v[200:203], v[76:79]
	v_mfma_f32_16x16x32_bf16 v[72:75], v[140:143], v[200:203], v[72:75]
	s_barrier
	s_add_i32 s39, s80, s33
	v_lshl_add_u64 v[176:177], s[6:7], 0, v[150:151]
	s_mov_b32 m0, s39
	ds_read_b128 v[204:207], v183
	ds_read_b128 v[210:213], v183 offset:1024
	ds_read_b128 v[214:217], v183 offset:2048
	ds_read_b128 v[218:221], v183 offset:3072
	global_load_lds_dwordx4 v[176:177], off
	v_lshl_add_u64 v[222:223], s[6:7], 0, v[154:155]
	s_add_i32 m0, s39, 0x2000
	s_nop 0
	global_load_lds_dwordx4 v[222:223], off
	s_barrier
	s_waitcnt lgkmcnt(0)
	s_waitcnt lgkmcnt(0)
	v_mfma_f32_16x16x32_bf16 v[116:119], v[204:207], v[144:147], v[116:119]
	v_mfma_f32_16x16x32_bf16 v[112:115], v[214:217], v[144:147], v[112:115]
	v_mfma_f32_16x16x32_bf16 v[100:103], v[204:207], v[172:175], v[100:103]
	v_mfma_f32_16x16x32_bf16 v[96:99], v[214:217], v[172:175], v[96:99]
	v_mfma_f32_16x16x32_bf16 v[84:87], v[204:207], v[188:191], v[84:87]
	v_mfma_f32_16x16x32_bf16 v[80:83], v[214:217], v[188:191], v[80:83]
	v_mfma_f32_16x16x32_bf16 v[68:71], v[204:207], v[196:199], v[68:71]
	v_mfma_f32_16x16x32_bf16 v[64:67], v[214:217], v[196:199], v[64:67]
	v_mfma_f32_16x16x32_bf16 v[116:119], v[210:213], v[168:171], v[116:119]
	v_mfma_f32_16x16x32_bf16 v[112:115], v[218:221], v[168:171], v[112:115]
	v_mfma_f32_16x16x32_bf16 v[100:103], v[210:213], v[184:187], v[100:103]
	v_mfma_f32_16x16x32_bf16 v[96:99], v[218:221], v[184:187], v[96:99]
	v_mfma_f32_16x16x32_bf16 v[84:87], v[210:213], v[192:195], v[84:87]
	v_mfma_f32_16x16x32_bf16 v[80:83], v[218:221], v[192:195], v[80:83]
	v_mfma_f32_16x16x32_bf16 v[68:71], v[210:213], v[200:203], v[68:71]
	v_mfma_f32_16x16x32_bf16 v[64:67], v[218:221], v[200:203], v[64:67]
	s_mov_b32 m0, s44
	v_lshl_add_u64 v[224:225], s[8:9], 0, v[148:149]
	s_barrier
	ds_read_b128 v[144:147], v182 offset:16384
	ds_read_b128 v[168:171], v182 offset:17408
	ds_read_b128 v[172:175], v182 offset:18432
	ds_read_b128 v[184:187], v182 offset:19456
	ds_read_b128 v[188:191], v182 offset:20480
	ds_read_b128 v[192:195], v182 offset:21504
	ds_read_b128 v[196:199], v182 offset:22528
	ds_read_b128 v[200:203], v182 offset:23552
	global_load_lds_dwordx4 v[224:225], off
	v_lshl_add_u64 v[226:227], s[8:9], 0, v[152:153]
	s_mov_b32 m0, s45
	s_nop 0
	global_load_lds_dwordx4 v[226:227], off
	s_waitcnt vmcnt(10)
	s_barrier
	s_waitcnt lgkmcnt(0)
	s_waitcnt lgkmcnt(0)
	v_mfma_f32_16x16x32_bf16 v[60:63], v[128:131], v[144:147], v[60:63]
	v_mfma_f32_16x16x32_bf16 v[56:59], v[136:139], v[144:147], v[56:59]
	v_mfma_f32_16x16x32_bf16 v[44:47], v[128:131], v[172:175], v[44:47]
	v_mfma_f32_16x16x32_bf16 v[40:43], v[136:139], v[172:175], v[40:43]
	v_mfma_f32_16x16x32_bf16 v[28:31], v[128:131], v[188:191], v[28:31]
	v_mfma_f32_16x16x32_bf16 v[24:27], v[136:139], v[188:191], v[24:27]
	v_mfma_f32_16x16x32_bf16 v[12:15], v[128:131], v[196:199], v[12:15]
	v_mfma_f32_16x16x32_bf16 v[8:11], v[136:139], v[196:199], v[8:11]
	v_mfma_f32_16x16x32_bf16 v[60:63], v[132:135], v[168:171], v[60:63]
	v_mfma_f32_16x16x32_bf16 v[56:59], v[140:143], v[168:171], v[56:59]
	v_mfma_f32_16x16x32_bf16 v[44:47], v[132:135], v[184:187], v[44:47]
	v_mfma_f32_16x16x32_bf16 v[40:43], v[140:143], v[184:187], v[40:43]
	v_mfma_f32_16x16x32_bf16 v[28:31], v[132:135], v[192:195], v[28:31]
	v_mfma_f32_16x16x32_bf16 v[24:27], v[140:143], v[192:195], v[24:27]
	v_mfma_f32_16x16x32_bf16 v[12:15], v[132:135], v[200:203], v[12:15]
	v_mfma_f32_16x16x32_bf16 v[8:11], v[140:143], v[200:203], v[8:11]
	s_barrier
	s_add_u32 s78, s6, 0x80000
	s_addc_u32 s79, s7, 0
	s_add_i32 s39, s81, s33
	v_lshl_add_u64 v[128:129], s[78:79], 0, v[150:151]
	s_mov_b32 m0, s39
	s_nop 0
	global_load_lds_dwordx4 v[128:129], off
	v_lshl_add_u64 v[128:129], s[78:79], 0, v[154:155]
	s_add_i32 m0, s39, 0x2000
	s_nop 0
	global_load_lds_dwordx4 v[128:129], off
	s_add_i32 s39, 0, 0x18000
	v_add_u32_e32 v140, s39, v180
	ds_read_b128 v[128:131], v140
	ds_read_b128 v[132:135], v140 offset:1024
	ds_read_b128 v[136:139], v140 offset:2048
	ds_read_b128 v[140:143], v140 offset:3072
	s_waitcnt vmcnt(6)
	s_barrier
	v_mfma_f32_16x16x32_bf16 v[52:55], v[204:207], v[144:147], v[52:55]
	v_mfma_f32_16x16x32_bf16 v[48:51], v[214:217], v[144:147], v[48:51]
	v_mfma_f32_16x16x32_bf16 v[36:39], v[204:207], v[172:175], v[36:39]
	v_mfma_f32_16x16x32_bf16 v[32:35], v[214:217], v[172:175], v[32:35]
	v_mfma_f32_16x16x32_bf16 v[20:23], v[204:207], v[188:191], v[20:23]
	v_mfma_f32_16x16x32_bf16 v[16:19], v[214:217], v[188:191], v[16:19]
	v_mfma_f32_16x16x32_bf16 v[4:7], v[204:207], v[196:199], v[4:7]
	v_mfma_f32_16x16x32_bf16 v[0:3], v[214:217], v[196:199], v[0:3]
	v_mfma_f32_16x16x32_bf16 v[52:55], v[210:213], v[168:171], v[52:55]
	v_mfma_f32_16x16x32_bf16 v[48:51], v[218:221], v[168:171], v[48:51]
	v_mfma_f32_16x16x32_bf16 v[36:39], v[210:213], v[184:187], v[36:39]
	v_mfma_f32_16x16x32_bf16 v[32:35], v[218:221], v[184:187], v[32:35]
	v_mfma_f32_16x16x32_bf16 v[20:23], v[210:213], v[192:195], v[20:23]
	v_mfma_f32_16x16x32_bf16 v[16:19], v[218:221], v[192:195], v[16:19]
	v_mfma_f32_16x16x32_bf16 v[4:7], v[210:213], v[200:203], v[4:7]
	v_mfma_f32_16x16x32_bf16 v[0:3], v[218:221], v[200:203], v[0:3]
	s_barrier
	s_add_u32 s8, s8, 0x80000
	s_addc_u32 s9, s9, 0
	s_mov_b32 m0, s51
	v_lshl_add_u64 v[204:205], s[8:9], 0, v[148:149]
	ds_read_b128 v[144:147], v182 offset:32768
	ds_read_b128 v[168:171], v182 offset:33792
	ds_read_b128 v[172:175], v182 offset:34816
	ds_read_b128 v[184:187], v182 offset:35840
	ds_read_b128 v[188:191], v182 offset:36864
	ds_read_b128 v[192:195], v182 offset:37888
	ds_read_b128 v[196:199], v182 offset:38912
	ds_read_b128 v[200:203], v182 offset:39936
	global_load_lds_dwordx4 v[204:205], off
	v_lshl_add_u64 v[204:205], s[8:9], 0, v[152:153]
	s_mov_b32 m0, s55
	s_nop 0
	global_load_lds_dwordx4 v[204:205], off
	s_waitcnt lgkmcnt(8)
	s_barrier
	s_waitcnt lgkmcnt(0)
	s_waitcnt lgkmcnt(0)
	v_mfma_f32_16x16x32_bf16 v[124:127], v[128:131], v[144:147], v[124:127]
	v_mfma_f32_16x16x32_bf16 v[120:123], v[136:139], v[144:147], v[120:123]
	v_mfma_f32_16x16x32_bf16 v[108:111], v[128:131], v[172:175], v[108:111]
	v_mfma_f32_16x16x32_bf16 v[104:107], v[136:139], v[172:175], v[104:107]
	v_mfma_f32_16x16x32_bf16 v[92:95], v[128:131], v[188:191], v[92:95]
	v_mfma_f32_16x16x32_bf16 v[88:91], v[136:139], v[188:191], v[88:91]
	v_mfma_f32_16x16x32_bf16 v[76:79], v[128:131], v[196:199], v[76:79]
	v_mfma_f32_16x16x32_bf16 v[72:75], v[136:139], v[196:199], v[72:75]
	v_mfma_f32_16x16x32_bf16 v[124:127], v[132:135], v[168:171], v[124:127]
	v_mfma_f32_16x16x32_bf16 v[120:123], v[140:143], v[168:171], v[120:123]
	v_mfma_f32_16x16x32_bf16 v[108:111], v[132:135], v[184:187], v[108:111]
	v_mfma_f32_16x16x32_bf16 v[104:107], v[140:143], v[184:187], v[104:107]
	v_mfma_f32_16x16x32_bf16 v[92:95], v[132:135], v[192:195], v[92:95]
	v_mfma_f32_16x16x32_bf16 v[88:91], v[140:143], v[192:195], v[88:91]
	v_mfma_f32_16x16x32_bf16 v[76:79], v[132:135], v[200:203], v[76:79]
	v_mfma_f32_16x16x32_bf16 v[72:75], v[140:143], v[200:203], v[72:75]
	s_barrier
	s_add_i32 s8, 0, 0x1c000
	s_add_i32 s9, s39, s33
	v_add_u32_e32 v156, s8, v180
	v_lshl_add_u64 v[176:177], v[176:177], 0, s[24:25]
	s_mov_b32 m0, s9
	ds_read_b128 v[204:207], v156
	ds_read_b128 v[210:213], v156 offset:1024
	ds_read_b128 v[214:217], v156 offset:2048
	ds_read_b128 v[218:221], v156 offset:3072
	global_load_lds_dwordx4 v[176:177], off
	v_lshl_add_u64 v[176:177], v[222:223], 0, s[24:25]
	s_add_i32 m0, s9, 0x2000
	s_nop 0
	global_load_lds_dwordx4 v[176:177], off
	s_barrier
	s_waitcnt lgkmcnt(0)
	s_waitcnt lgkmcnt(0)
	v_mfma_f32_16x16x32_bf16 v[116:119], v[204:207], v[144:147], v[116:119]
	v_mfma_f32_16x16x32_bf16 v[112:115], v[214:217], v[144:147], v[112:115]
	v_mfma_f32_16x16x32_bf16 v[100:103], v[204:207], v[172:175], v[100:103]
	v_mfma_f32_16x16x32_bf16 v[96:99], v[214:217], v[172:175], v[96:99]
	v_mfma_f32_16x16x32_bf16 v[84:87], v[204:207], v[188:191], v[84:87]
	v_mfma_f32_16x16x32_bf16 v[80:83], v[214:217], v[188:191], v[80:83]
	v_mfma_f32_16x16x32_bf16 v[68:71], v[204:207], v[196:199], v[68:71]
	v_mfma_f32_16x16x32_bf16 v[64:67], v[214:217], v[196:199], v[64:67]
	v_mfma_f32_16x16x32_bf16 v[116:119], v[210:213], v[168:171], v[116:119]
	v_mfma_f32_16x16x32_bf16 v[112:115], v[218:221], v[168:171], v[112:115]
	v_mfma_f32_16x16x32_bf16 v[100:103], v[210:213], v[184:187], v[100:103]
	v_mfma_f32_16x16x32_bf16 v[96:99], v[218:221], v[184:187], v[96:99]
	v_mfma_f32_16x16x32_bf16 v[84:87], v[210:213], v[192:195], v[84:87]
	v_mfma_f32_16x16x32_bf16 v[80:83], v[218:221], v[192:195], v[80:83]
	v_mfma_f32_16x16x32_bf16 v[68:71], v[210:213], v[200:203], v[68:71]
	v_mfma_f32_16x16x32_bf16 v[64:67], v[218:221], v[200:203], v[64:67]
	s_mov_b32 m0, s83
	v_lshl_add_u64 v[176:177], v[224:225], 0, s[24:25]
	s_barrier
	ds_read_b128 v[144:147], v182 offset:49152
	ds_read_b128 v[168:171], v182 offset:50176
	ds_read_b128 v[172:175], v182 offset:51200
	ds_read_b128 v[184:187], v182 offset:52224
	ds_read_b128 v[188:191], v182 offset:53248
	ds_read_b128 v[192:195], v182 offset:54272
	ds_read_b128 v[196:199], v182 offset:55296
	ds_read_b128 v[200:203], v182 offset:56320
	global_load_lds_dwordx4 v[176:177], off
	v_lshl_add_u64 v[176:177], v[226:227], 0, s[24:25]
	s_mov_b32 m0, s91
	s_nop 0
	global_load_lds_dwordx4 v[176:177], off
	s_waitcnt vmcnt(10)
	s_barrier
	s_waitcnt lgkmcnt(0)
	s_waitcnt lgkmcnt(0)
	v_mfma_f32_16x16x32_bf16 v[60:63], v[128:131], v[144:147], v[60:63]
	v_mfma_f32_16x16x32_bf16 v[56:59], v[136:139], v[144:147], v[56:59]
	v_mfma_f32_16x16x32_bf16 v[44:47], v[128:131], v[172:175], v[44:47]
	v_mfma_f32_16x16x32_bf16 v[40:43], v[136:139], v[172:175], v[40:43]
	v_mfma_f32_16x16x32_bf16 v[28:31], v[128:131], v[188:191], v[28:31]
	v_mfma_f32_16x16x32_bf16 v[24:27], v[136:139], v[188:191], v[24:27]
	v_mfma_f32_16x16x32_bf16 v[12:15], v[128:131], v[196:199], v[12:15]
	v_mfma_f32_16x16x32_bf16 v[8:11], v[136:139], v[196:199], v[8:11]
	v_mfma_f32_16x16x32_bf16 v[60:63], v[132:135], v[168:171], v[60:63]
	v_mfma_f32_16x16x32_bf16 v[56:59], v[140:143], v[168:171], v[56:59]
	v_mfma_f32_16x16x32_bf16 v[44:47], v[132:135], v[184:187], v[44:47]
	v_mfma_f32_16x16x32_bf16 v[40:43], v[140:143], v[184:187], v[40:43]
	v_mfma_f32_16x16x32_bf16 v[28:31], v[132:135], v[192:195], v[28:31]
	v_mfma_f32_16x16x32_bf16 v[24:27], v[140:143], v[192:195], v[24:27]
	v_mfma_f32_16x16x32_bf16 v[12:15], v[132:135], v[200:203], v[12:15]
	v_mfma_f32_16x16x32_bf16 v[8:11], v[140:143], v[200:203], v[8:11]
	s_barrier
	s_add_u32 s6, s6, 0x80080
	s_addc_u32 s7, s7, 0
	s_add_i32 s8, s8, s33
	v_lshl_add_u64 v[128:129], s[6:7], 0, v[150:151]
	s_mov_b32 m0, s8
	s_nop 0
	global_load_lds_dwordx4 v[128:129], off
	v_lshl_add_u64 v[128:129], s[6:7], 0, v[154:155]
	s_add_i32 m0, s8, 0x2000
	s_nop 0
	global_load_lds_dwordx4 v[128:129], off
	ds_read_b128 v[128:131], v181
	ds_read_b128 v[132:135], v181 offset:1024
	ds_read_b128 v[136:139], v181 offset:2048
	ds_read_b128 v[140:143], v181 offset:3072
	s_waitcnt vmcnt(6)
	s_barrier
	s_waitcnt lgkmcnt(0)
	v_mfma_f32_16x16x32_bf16 v[52:55], v[204:207], v[144:147], v[52:55]
	v_mfma_f32_16x16x32_bf16 v[48:51], v[214:217], v[144:147], v[48:51]
	v_mfma_f32_16x16x32_bf16 v[36:39], v[204:207], v[172:175], v[36:39]
	v_mfma_f32_16x16x32_bf16 v[32:35], v[214:217], v[172:175], v[32:35]
	v_mfma_f32_16x16x32_bf16 v[20:23], v[204:207], v[188:191], v[20:23]
	v_mfma_f32_16x16x32_bf16 v[16:19], v[214:217], v[188:191], v[16:19]
	v_mfma_f32_16x16x32_bf16 v[4:7], v[204:207], v[196:199], v[4:7]
	v_mfma_f32_16x16x32_bf16 v[0:3], v[214:217], v[196:199], v[0:3]
	v_mfma_f32_16x16x32_bf16 v[52:55], v[210:213], v[168:171], v[52:55]
	v_mfma_f32_16x16x32_bf16 v[48:51], v[218:221], v[168:171], v[48:51]
	v_mfma_f32_16x16x32_bf16 v[36:39], v[210:213], v[184:187], v[36:39]
	v_mfma_f32_16x16x32_bf16 v[32:35], v[218:221], v[184:187], v[32:35]
	v_mfma_f32_16x16x32_bf16 v[20:23], v[210:213], v[192:195], v[20:23]
	v_mfma_f32_16x16x32_bf16 v[16:19], v[218:221], v[192:195], v[16:19]
	v_mfma_f32_16x16x32_bf16 v[4:7], v[210:213], v[200:203], v[4:7]
	v_mfma_f32_16x16x32_bf16 v[0:3], v[218:221], v[200:203], v[0:3]
	s_add_i32 s37, s37, 2
	s_add_u32 s4, s4, 0x100
	s_addc_u32 s5, s5, 0
	s_add_u32 s35, s35, 0x100
	s_addc_u32 s36, s36, 0
	s_cmp_gt_u32 s37, 29
	s_barrier
	s_cbranch_scc0 .LBB0_262
	v_mov_b32_e32 v185, v179
	v_mov_b32_e32 v184, v178
	s_cmp_lt_i32 s90, 33
	s_mov_b64 s[4:5], -1
	s_cbranch_scc0 .LBB0_589
	s_cmp_gt_i32 s82, 3
	s_cbranch_scc0 .LBB0_586
	s_cmp_gt_u32 s82, 7
	s_cbranch_scc0 .LBB0_551
	s_cmp_gt_u32 s82, 15
	s_cbranch_scc0 .LBB0_548
	s_cmp_gt_u32 s82, 23
	s_cbranch_scc0 .LBB0_545
	s_cmp_gt_u32 s82, 27
	s_cbranch_scc0 .LBB0_486
	s_cmp_gt_u32 s82, 31
	s_cbranch_scc0 .LBB0_315
	s_cmp_gt_u32 s82, 35
	s_cbranch_scc0 .LBB0_280
	s_cmp_gt_u32 s82, 39
	s_cbranch_scc0 .LBB0_277
	s_lshl_b32 s4, s90, 8
	s_add_i32 s4, s4, s57
	v_lshl_add_u32 v128, v185, 3, s59
	v_add_u32_e32 v132, s4, v184
	v_ashrrev_i32_e32 v129, 31, v128
	v_mad_i64_i32 v[130:131], s[4:5], v132, s28, 0
	s_cmp_gt_u32 s82, 41
	s_mov_b64 s[4:5], -1
	v_lshl_add_u64 v[130:131], s[0:1], 0, v[130:131]
	v_lshlrev_b64 v[128:129], 1, v[128:129]
	v_add_u32_e32 v138, 16, v132
	v_add_u32_e32 v137, 32, v132
	v_add_u32_e32 v136, 48, v132
	v_add_u32_e32 v135, 0x80, v132
	v_add_u32_e32 v134, 0x90, v132
	v_add_u32_e32 v133, 0xa0, v132
	v_add_u32_e32 v132, 0xb0, v132
	s_cbranch_scc0 .LBB0_274
	s_lshl_b32 s20, s82, 8
	s_lshl_b64 s[4:5], s[20:21], 1
	v_lshl_add_u64 v[144:145], v[130:131], 0, s[4:5]
	v_cvt_pk_bf16_f32 v140, v124, v125
	v_cvt_pk_bf16_f32 v141, v126, v127
	v_cvt_pk_bf16_f32 v142, v120, v121
	v_cvt_pk_bf16_f32 v143, v122, v123
	v_lshl_add_u64 v[144:145], v[144:145], 0, v[128:129]
	global_store_dwordx4 v[144:145], v[140:143], off
	s_nop 1
	v_cvt_pk_bf16_f32 v140, v116, v117
	v_cvt_pk_bf16_f32 v141, v118, v119
	v_cvt_pk_bf16_f32 v142, v112, v113
	v_cvt_pk_bf16_f32 v143, v114, v115
	global_store_dwordx4 v[144:145], v[140:143], off offset:256
	v_mov_b64_e32 v[144:145], s[0:1]
	v_mad_i64_i32 v[146:147], s[6:7], v138, s28, v[144:145]
	v_lshl_add_u64 v[146:147], v[146:147], 0, s[4:5]
	v_cvt_pk_bf16_f32 v140, v108, v109
	v_cvt_pk_bf16_f32 v141, v110, v111
	v_cvt_pk_bf16_f32 v142, v104, v105
	v_cvt_pk_bf16_f32 v143, v106, v107
	v_lshl_add_u64 v[146:147], v[146:147], 0, v[128:129]
	global_store_dwordx4 v[146:147], v[140:143], off
	s_nop 1
	v_cvt_pk_bf16_f32 v140, v100, v101
	v_cvt_pk_bf16_f32 v141, v102, v103
	v_cvt_pk_bf16_f32 v142, v96, v97
	v_cvt_pk_bf16_f32 v143, v98, v99
	global_store_dwordx4 v[146:147], v[140:143], off offset:256
	v_mad_i64_i32 v[146:147], s[6:7], v137, s28, v[144:145]
	v_lshl_add_u64 v[146:147], v[146:147], 0, s[4:5]
	v_cvt_pk_bf16_f32 v140, v92, v93
	v_cvt_pk_bf16_f32 v141, v94, v95
	v_cvt_pk_bf16_f32 v142, v88, v89
	v_cvt_pk_bf16_f32 v143, v90, v91
	v_lshl_add_u64 v[146:147], v[146:147], 0, v[128:129]
	global_store_dwordx4 v[146:147], v[140:143], off
	s_nop 1
	v_cvt_pk_bf16_f32 v140, v84, v85
	v_cvt_pk_bf16_f32 v141, v86, v87
	v_cvt_pk_bf16_f32 v142, v80, v81
	v_cvt_pk_bf16_f32 v143, v82, v83
	global_store_dwordx4 v[146:147], v[140:143], off offset:256
	v_mad_i64_i32 v[146:147], s[6:7], v136, s28, v[144:145]
	v_lshl_add_u64 v[146:147], v[146:147], 0, s[4:5]
	v_cvt_pk_bf16_f32 v140, v76, v77
	v_cvt_pk_bf16_f32 v141, v78, v79
	v_cvt_pk_bf16_f32 v142, v72, v73
	v_cvt_pk_bf16_f32 v143, v74, v75
	v_lshl_add_u64 v[146:147], v[146:147], 0, v[128:129]
	global_store_dwordx4 v[146:147], v[140:143], off
	s_nop 1
	v_cvt_pk_bf16_f32 v140, v68, v69
	v_cvt_pk_bf16_f32 v141, v70, v71
	v_cvt_pk_bf16_f32 v142, v64, v65
	v_cvt_pk_bf16_f32 v143, v66, v67
	global_store_dwordx4 v[146:147], v[140:143], off offset:256
	v_mad_i64_i32 v[146:147], s[6:7], v135, s28, v[144:145]
	v_lshl_add_u64 v[146:147], v[146:147], 0, s[4:5]
	v_cvt_pk_bf16_f32 v140, v60, v61
	v_cvt_pk_bf16_f32 v141, v62, v63
	v_cvt_pk_bf16_f32 v142, v56, v57
	v_cvt_pk_bf16_f32 v143, v58, v59
	v_lshl_add_u64 v[146:147], v[146:147], 0, v[128:129]
	global_store_dwordx4 v[146:147], v[140:143], off
	s_nop 1
	v_cvt_pk_bf16_f32 v140, v52, v53
	v_cvt_pk_bf16_f32 v141, v54, v55
	v_cvt_pk_bf16_f32 v142, v48, v49
	v_cvt_pk_bf16_f32 v143, v50, v51
	global_store_dwordx4 v[146:147], v[140:143], off offset:256
	v_mad_i64_i32 v[146:147], s[6:7], v134, s28, v[144:145]
	v_lshl_add_u64 v[146:147], v[146:147], 0, s[4:5]
	v_cvt_pk_bf16_f32 v140, v44, v45
	v_cvt_pk_bf16_f32 v141, v46, v47
	v_cvt_pk_bf16_f32 v142, v40, v41
	v_cvt_pk_bf16_f32 v143, v42, v43
	v_lshl_add_u64 v[146:147], v[146:147], 0, v[128:129]
	global_store_dwordx4 v[146:147], v[140:143], off
	s_nop 1
	v_cvt_pk_bf16_f32 v140, v36, v37
	v_cvt_pk_bf16_f32 v141, v38, v39
	v_cvt_pk_bf16_f32 v142, v32, v33
	v_cvt_pk_bf16_f32 v143, v34, v35
	global_store_dwordx4 v[146:147], v[140:143], off offset:256
	v_mad_i64_i32 v[146:147], s[6:7], v133, s28, v[144:145]
	v_lshl_add_u64 v[146:147], v[146:147], 0, s[4:5]
	v_cvt_pk_bf16_f32 v140, v28, v29
	v_cvt_pk_bf16_f32 v141, v30, v31
	v_cvt_pk_bf16_f32 v142, v24, v25
	v_cvt_pk_bf16_f32 v143, v26, v27
	v_lshl_add_u64 v[146:147], v[146:147], 0, v[128:129]
	v_mad_i64_i32 v[144:145], s[6:7], v132, s28, v[144:145]
	global_store_dwordx4 v[146:147], v[140:143], off
	v_lshl_add_u64 v[144:145], v[144:145], 0, s[4:5]
	v_lshl_add_u64 v[144:145], v[144:145], 0, v[128:129]
	v_cvt_pk_bf16_f32 v140, v20, v21
	v_cvt_pk_bf16_f32 v141, v22, v23
	v_cvt_pk_bf16_f32 v142, v16, v17
	v_cvt_pk_bf16_f32 v143, v18, v19
	global_store_dwordx4 v[146:147], v[140:143], off offset:256
	s_mov_b64 s[4:5], 0
	s_nop 0
	v_cvt_pk_bf16_f32 v140, v12, v13
	v_cvt_pk_bf16_f32 v141, v14, v15
	v_cvt_pk_bf16_f32 v142, v8, v9
	v_cvt_pk_bf16_f32 v143, v10, v11
	global_store_dwordx4 v[144:145], v[140:143], off
	s_nop 1
	v_cvt_pk_bf16_f32 v140, v4, v5
	v_cvt_pk_bf16_f32 v141, v6, v7
	v_cvt_pk_bf16_f32 v142, v0, v1
	v_cvt_pk_bf16_f32 v143, v2, v3
	global_store_dwordx4 v[144:145], v[140:143], off offset:256

.LBB0_974:
	s_add_u32 s16, s14, 0x100
	s_addc_u32 s17, s15, 0
	s_cmp_eq_u32 s44, 52
	s_cselect_b32 s21, s3, s17
	s_cselect_b32 s20, s2, s16
	s_cselect_b32 s19, s5, s43
	s_cselect_b32 s18, s4, s42
	v_lshl_add_u64 v[198:199], s[14:15], 0, v[136:137]
	s_add_i32 m0, s24, 0xc000
	ds_read_b128 v[166:169], v148
	ds_read_b128 v[170:173], v148 offset:1024
	ds_read_b128 v[174:177], v148 offset:2048
	ds_read_b128 v[178:181], v148 offset:3072
	ds_read_b128 v[182:185], v148 offset:4096
	ds_read_b128 v[186:189], v148 offset:5120
	ds_read_b128 v[190:193], v148 offset:6144
	ds_read_b128 v[194:197], v148 offset:7168
	global_load_lds_dwordx4 v[198:199], off
	v_lshl_add_u64 v[198:199], s[14:15], 0, v[138:139]
	s_add_i32 m0, s24, 0xe000
	s_nop 0
	global_load_lds_dwordx4 v[198:199], off
	s_waitcnt lgkmcnt(8)
	s_barrier
	s_waitcnt lgkmcnt(0)
	s_waitcnt lgkmcnt(0)
	v_mfma_f32_16x16x32_bf16 v[124:127], v[150:153], v[166:169], v[124:127]
	v_mfma_f32_16x16x32_bf16 v[120:123], v[158:161], v[166:169], v[120:123]
	v_mfma_f32_16x16x32_bf16 v[116:119], v[150:153], v[174:177], v[116:119]
	v_mfma_f32_16x16x32_bf16 v[112:115], v[158:161], v[174:177], v[112:115]
	v_mfma_f32_16x16x32_bf16 v[100:103], v[150:153], v[182:185], v[100:103]
	v_mfma_f32_16x16x32_bf16 v[96:99], v[158:161], v[182:185], v[96:99]
	v_mfma_f32_16x16x32_bf16 v[84:87], v[150:153], v[190:193], v[84:87]
	v_mfma_f32_16x16x32_bf16 v[80:83], v[158:161], v[190:193], v[80:83]
	v_mfma_f32_16x16x32_bf16 v[124:127], v[154:157], v[170:173], v[124:127]
	v_mfma_f32_16x16x32_bf16 v[120:123], v[162:165], v[170:173], v[120:123]
	v_mfma_f32_16x16x32_bf16 v[116:119], v[154:157], v[178:181], v[116:119]
	v_mfma_f32_16x16x32_bf16 v[112:115], v[162:165], v[178:181], v[112:115]
	v_mfma_f32_16x16x32_bf16 v[100:103], v[154:157], v[186:189], v[100:103]
	v_mfma_f32_16x16x32_bf16 v[96:99], v[162:165], v[186:189], v[96:99]
	v_mfma_f32_16x16x32_bf16 v[84:87], v[154:157], v[194:197], v[84:87]
	v_mfma_f32_16x16x32_bf16 v[80:83], v[162:165], v[194:197], v[80:83]
	s_barrier
	s_add_i32 s14, s35, s23
	v_lshl_add_u64 v[206:207], s[18:19], 0, v[130:131]
	s_mov_b32 m0, s14
	ds_read_b128 v[198:201], v149
	ds_read_b128 v[202:205], v149 offset:1024
	ds_read_b128 v[210:213], v149 offset:2048
	ds_read_b128 v[214:217], v149 offset:3072
	global_load_lds_dwordx4 v[206:207], off
	v_lshl_add_u64 v[218:219], s[18:19], 0, v[134:135]
	s_add_i32 m0, s14, 0x2000
	s_nop 0
	global_load_lds_dwordx4 v[218:219], off
	s_barrier
	s_waitcnt lgkmcnt(0)
	s_waitcnt lgkmcnt(0)
	v_mfma_f32_16x16x32_bf16 v[108:111], v[198:201], v[166:169], v[108:111]
	v_mfma_f32_16x16x32_bf16 v[104:107], v[210:213], v[166:169], v[104:107]
	v_mfma_f32_16x16x32_bf16 v[92:95], v[198:201], v[174:177], v[92:95]
	v_mfma_f32_16x16x32_bf16 v[88:91], v[210:213], v[174:177], v[88:91]
	v_mfma_f32_16x16x32_bf16 v[76:79], v[198:201], v[182:185], v[76:79]
	v_mfma_f32_16x16x32_bf16 v[72:75], v[210:213], v[182:185], v[72:75]
	v_mfma_f32_16x16x32_bf16 v[68:71], v[198:201], v[190:193], v[68:71]
	v_mfma_f32_16x16x32_bf16 v[64:67], v[210:213], v[190:193], v[64:67]
	v_mfma_f32_16x16x32_bf16 v[108:111], v[202:205], v[170:173], v[108:111]
	v_mfma_f32_16x16x32_bf16 v[104:107], v[214:217], v[170:173], v[104:107]
	v_mfma_f32_16x16x32_bf16 v[92:95], v[202:205], v[178:181], v[92:95]
	v_mfma_f32_16x16x32_bf16 v[88:91], v[214:217], v[178:181], v[88:91]
	v_mfma_f32_16x16x32_bf16 v[76:79], v[202:205], v[186:189], v[76:79]
	v_mfma_f32_16x16x32_bf16 v[72:75], v[214:217], v[186:189], v[72:75]
	v_mfma_f32_16x16x32_bf16 v[68:71], v[202:205], v[194:197], v[68:71]
	v_mfma_f32_16x16x32_bf16 v[64:67], v[214:217], v[194:197], v[64:67]
	s_mov_b32 m0, s24
	v_lshl_add_u64 v[220:221], s[20:21], 0, v[128:129]
	s_barrier
	ds_read_b128 v[166:169], v148 offset:16384
	ds_read_b128 v[170:173], v148 offset:17408
	ds_read_b128 v[174:177], v148 offset:18432
	ds_read_b128 v[178:181], v148 offset:19456
	ds_read_b128 v[182:185], v148 offset:20480
	ds_read_b128 v[186:189], v148 offset:21504
	ds_read_b128 v[190:193], v148 offset:22528
	ds_read_b128 v[194:197], v148 offset:23552
	global_load_lds_dwordx4 v[220:221], off
	v_lshl_add_u64 v[222:223], s[20:21], 0, v[132:133]
	s_mov_b32 m0, s25
	s_nop 0
	global_load_lds_dwordx4 v[222:223], off
	s_waitcnt vmcnt(10)
	s_barrier
	s_waitcnt lgkmcnt(0)
	s_waitcnt lgkmcnt(0)
	v_mfma_f32_16x16x32_bf16 v[60:63], v[150:153], v[166:169], v[60:63]
	v_mfma_f32_16x16x32_bf16 v[56:59], v[158:161], v[166:169], v[56:59]
	v_mfma_f32_16x16x32_bf16 v[52:55], v[150:153], v[174:177], v[52:55]
	v_mfma_f32_16x16x32_bf16 v[48:51], v[158:161], v[174:177], v[48:51]
	v_mfma_f32_16x16x32_bf16 v[36:39], v[150:153], v[182:185], v[36:39]
	v_mfma_f32_16x16x32_bf16 v[32:35], v[158:161], v[182:185], v[32:35]
	v_mfma_f32_16x16x32_bf16 v[20:23], v[150:153], v[190:193], v[20:23]
	v_mfma_f32_16x16x32_bf16 v[16:19], v[158:161], v[190:193], v[16:19]
	v_mfma_f32_16x16x32_bf16 v[60:63], v[154:157], v[170:173], v[60:63]
	v_mfma_f32_16x16x32_bf16 v[56:59], v[162:165], v[170:173], v[56:59]
	v_mfma_f32_16x16x32_bf16 v[52:55], v[154:157], v[178:181], v[52:55]
	v_mfma_f32_16x16x32_bf16 v[48:51], v[162:165], v[178:181], v[48:51]
	v_mfma_f32_16x16x32_bf16 v[36:39], v[154:157], v[186:189], v[36:39]
	v_mfma_f32_16x16x32_bf16 v[32:35], v[162:165], v[186:189], v[32:35]
	v_mfma_f32_16x16x32_bf16 v[20:23], v[154:157], v[194:197], v[20:23]
	v_mfma_f32_16x16x32_bf16 v[16:19], v[162:165], v[194:197], v[16:19]
	s_barrier
	s_add_u32 s14, s18, 0xe0000
	s_addc_u32 s15, s19, 0
	s_add_i32 s45, s36, s23
	v_lshl_add_u64 v[150:151], s[14:15], 0, v[130:131]
	s_mov_b32 m0, s45
	s_nop 0
	global_load_lds_dwordx4 v[150:151], off
	v_lshl_add_u64 v[150:151], s[14:15], 0, v[134:135]
	s_add_i32 m0, s45, 0x2000
	s_nop 0
	global_load_lds_dwordx4 v[150:151], off
	s_add_i32 s45, 0, 0x18000
	v_add_u32_e32 v162, s45, v146
	ds_read_b128 v[150:153], v162
	ds_read_b128 v[154:157], v162 offset:1024
	ds_read_b128 v[158:161], v162 offset:2048
	ds_read_b128 v[162:165], v162 offset:3072
	s_waitcnt vmcnt(6)
	s_barrier
	v_mfma_f32_16x16x32_bf16 v[44:47], v[198:201], v[166:169], v[44:47]
	v_mfma_f32_16x16x32_bf16 v[40:43], v[210:213], v[166:169], v[40:43]
	v_mfma_f32_16x16x32_bf16 v[28:31], v[198:201], v[174:177], v[28:31]
	v_mfma_f32_16x16x32_bf16 v[24:27], v[210:213], v[174:177], v[24:27]
	v_mfma_f32_16x16x32_bf16 v[12:15], v[198:201], v[182:185], v[12:15]
	v_mfma_f32_16x16x32_bf16 v[8:11], v[210:213], v[182:185], v[8:11]
	v_mfma_f32_16x16x32_bf16 v[4:7], v[198:201], v[190:193], v[4:7]
	v_mfma_f32_16x16x32_bf16 v[0:3], v[210:213], v[190:193], v[0:3]
	v_mfma_f32_16x16x32_bf16 v[44:47], v[202:205], v[170:173], v[44:47]
	v_mfma_f32_16x16x32_bf16 v[40:43], v[214:217], v[170:173], v[40:43]
	v_mfma_f32_16x16x32_bf16 v[28:31], v[202:205], v[178:181], v[28:31]
	v_mfma_f32_16x16x32_bf16 v[24:27], v[214:217], v[178:181], v[24:27]
	v_mfma_f32_16x16x32_bf16 v[12:15], v[202:205], v[186:189], v[12:15]
	v_mfma_f32_16x16x32_bf16 v[8:11], v[214:217], v[186:189], v[8:11]
	v_mfma_f32_16x16x32_bf16 v[4:7], v[202:205], v[194:197], v[4:7]
	v_mfma_f32_16x16x32_bf16 v[0:3], v[214:217], v[194:197], v[0:3]
	s_barrier
	s_add_u32 s14, s20, 0xe0000
	s_addc_u32 s15, s21, 0
	s_mov_b32 m0, s26
	v_lshl_add_u64 v[198:199], s[14:15], 0, v[128:129]
	ds_read_b128 v[166:169], v148 offset:32768
	ds_read_b128 v[170:173], v148 offset:33792
	ds_read_b128 v[174:177], v148 offset:34816
	ds_read_b128 v[178:181], v148 offset:35840
	ds_read_b128 v[182:185], v148 offset:36864
	ds_read_b128 v[186:189], v148 offset:37888
	ds_read_b128 v[190:193], v148 offset:38912
	ds_read_b128 v[194:197], v148 offset:39936
	global_load_lds_dwordx4 v[198:199], off
	v_lshl_add_u64 v[198:199], s[14:15], 0, v[132:133]
	s_mov_b32 m0, s27
	s_nop 0
	global_load_lds_dwordx4 v[198:199], off
	s_waitcnt lgkmcnt(8)
	s_barrier
	s_waitcnt lgkmcnt(0)
	s_waitcnt lgkmcnt(0)
	v_mfma_f32_16x16x32_bf16 v[124:127], v[150:153], v[166:169], v[124:127]
	v_mfma_f32_16x16x32_bf16 v[120:123], v[158:161], v[166:169], v[120:123]
	v_mfma_f32_16x16x32_bf16 v[116:119], v[150:153], v[174:177], v[116:119]
	v_mfma_f32_16x16x32_bf16 v[112:115], v[158:161], v[174:177], v[112:115]
	v_mfma_f32_16x16x32_bf16 v[100:103], v[150:153], v[182:185], v[100:103]
	v_mfma_f32_16x16x32_bf16 v[96:99], v[158:161], v[182:185], v[96:99]
	v_mfma_f32_16x16x32_bf16 v[84:87], v[150:153], v[190:193], v[84:87]
	v_mfma_f32_16x16x32_bf16 v[80:83], v[158:161], v[190:193], v[80:83]
	v_mfma_f32_16x16x32_bf16 v[124:127], v[154:157], v[170:173], v[124:127]
	v_mfma_f32_16x16x32_bf16 v[120:123], v[162:165], v[170:173], v[120:123]
	v_mfma_f32_16x16x32_bf16 v[116:119], v[154:157], v[178:181], v[116:119]
	v_mfma_f32_16x16x32_bf16 v[112:115], v[162:165], v[178:181], v[112:115]
	v_mfma_f32_16x16x32_bf16 v[100:103], v[154:157], v[186:189], v[100:103]
	v_mfma_f32_16x16x32_bf16 v[96:99], v[162:165], v[186:189], v[96:99]
	v_mfma_f32_16x16x32_bf16 v[84:87], v[154:157], v[194:197], v[84:87]
	v_mfma_f32_16x16x32_bf16 v[80:83], v[162:165], v[194:197], v[80:83]
	s_barrier
	s_add_i32 s20, 0, 0x1c000
	s_add_i32 s14, s45, s23
	v_add_u32_e32 v214, s20, v146
	v_lshl_add_u64 v[206:207], v[206:207], 0, s[8:9]
	s_mov_b32 m0, s14
	ds_read_b128 v[198:201], v214
	ds_read_b128 v[202:205], v214 offset:1024
	ds_read_b128 v[210:213], v214 offset:2048
	ds_read_b128 v[214:217], v214 offset:3072
	global_load_lds_dwordx4 v[206:207], off
	v_lshl_add_u64 v[206:207], v[218:219], 0, s[8:9]
	s_add_i32 m0, s14, 0x2000
	s_nop 0
	global_load_lds_dwordx4 v[206:207], off
	s_barrier
	s_waitcnt lgkmcnt(0)
	s_waitcnt lgkmcnt(0)
	v_mfma_f32_16x16x32_bf16 v[108:111], v[198:201], v[166:169], v[108:111]
	v_mfma_f32_16x16x32_bf16 v[104:107], v[210:213], v[166:169], v[104:107]
	v_mfma_f32_16x16x32_bf16 v[92:95], v[198:201], v[174:177], v[92:95]
	v_mfma_f32_16x16x32_bf16 v[88:91], v[210:213], v[174:177], v[88:91]
	v_mfma_f32_16x16x32_bf16 v[76:79], v[198:201], v[182:185], v[76:79]
	v_mfma_f32_16x16x32_bf16 v[72:75], v[210:213], v[182:185], v[72:75]
	v_mfma_f32_16x16x32_bf16 v[68:71], v[198:201], v[190:193], v[68:71]
	v_mfma_f32_16x16x32_bf16 v[64:67], v[210:213], v[190:193], v[64:67]
	v_mfma_f32_16x16x32_bf16 v[108:111], v[202:205], v[170:173], v[108:111]
	v_mfma_f32_16x16x32_bf16 v[104:107], v[214:217], v[170:173], v[104:107]
	v_mfma_f32_16x16x32_bf16 v[92:95], v[202:205], v[178:181], v[92:95]
	v_mfma_f32_16x16x32_bf16 v[88:91], v[214:217], v[178:181], v[88:91]
	v_mfma_f32_16x16x32_bf16 v[76:79], v[202:205], v[186:189], v[76:79]
	v_mfma_f32_16x16x32_bf16 v[72:75], v[214:217], v[186:189], v[72:75]
	v_mfma_f32_16x16x32_bf16 v[68:71], v[202:205], v[194:197], v[68:71]
	v_mfma_f32_16x16x32_bf16 v[64:67], v[214:217], v[194:197], v[64:67]
	s_mov_b32 m0, s31
	v_lshl_add_u64 v[206:207], v[220:221], 0, s[8:9]
	s_barrier
	ds_read_b128 v[166:169], v148 offset:49152
	ds_read_b128 v[170:173], v148 offset:50176
	ds_read_b128 v[174:177], v148 offset:51200
	ds_read_b128 v[178:181], v148 offset:52224
	ds_read_b128 v[182:185], v148 offset:53248
	ds_read_b128 v[186:189], v148 offset:54272
	ds_read_b128 v[190:193], v148 offset:55296
	ds_read_b128 v[194:197], v148 offset:56320
	global_load_lds_dwordx4 v[206:207], off
	v_lshl_add_u64 v[206:207], v[222:223], 0, s[8:9]
	s_mov_b32 m0, s33
	s_nop 0
	global_load_lds_dwordx4 v[206:207], off
	s_waitcnt vmcnt(10)
	s_barrier
	s_waitcnt lgkmcnt(0)
	s_waitcnt lgkmcnt(0)
	v_mfma_f32_16x16x32_bf16 v[60:63], v[150:153], v[166:169], v[60:63]
	v_mfma_f32_16x16x32_bf16 v[56:59], v[158:161], v[166:169], v[56:59]
	v_mfma_f32_16x16x32_bf16 v[52:55], v[150:153], v[174:177], v[52:55]
	v_mfma_f32_16x16x32_bf16 v[48:51], v[158:161], v[174:177], v[48:51]
	v_mfma_f32_16x16x32_bf16 v[36:39], v[150:153], v[182:185], v[36:39]
	v_mfma_f32_16x16x32_bf16 v[32:35], v[158:161], v[182:185], v[32:35]
	v_mfma_f32_16x16x32_bf16 v[20:23], v[150:153], v[190:193], v[20:23]
	v_mfma_f32_16x16x32_bf16 v[16:19], v[158:161], v[190:193], v[16:19]
	v_mfma_f32_16x16x32_bf16 v[60:63], v[154:157], v[170:173], v[60:63]
	v_mfma_f32_16x16x32_bf16 v[56:59], v[162:165], v[170:173], v[56:59]
	v_mfma_f32_16x16x32_bf16 v[52:55], v[154:157], v[178:181], v[52:55]
	v_mfma_f32_16x16x32_bf16 v[48:51], v[162:165], v[178:181], v[48:51]
	v_mfma_f32_16x16x32_bf16 v[36:39], v[154:157], v[186:189], v[36:39]
	v_mfma_f32_16x16x32_bf16 v[32:35], v[162:165], v[186:189], v[32:35]
	v_mfma_f32_16x16x32_bf16 v[20:23], v[154:157], v[194:197], v[20:23]
	v_mfma_f32_16x16x32_bf16 v[16:19], v[162:165], v[194:197], v[16:19]
	s_barrier
	s_add_u32 s14, s18, 0xe0080
	s_addc_u32 s15, s19, 0
	s_add_i32 s18, s20, s23
	v_lshl_add_u64 v[150:151], s[14:15], 0, v[130:131]
	s_mov_b32 m0, s18
	s_nop 0
	global_load_lds_dwordx4 v[150:151], off
	v_lshl_add_u64 v[150:151], s[14:15], 0, v[134:135]
	s_add_i32 m0, s18, 0x2000
	s_nop 0
	global_load_lds_dwordx4 v[150:151], off
	ds_read_b128 v[150:153], v147
	ds_read_b128 v[154:157], v147 offset:1024
	ds_read_b128 v[158:161], v147 offset:2048
	ds_read_b128 v[162:165], v147 offset:3072
	s_waitcnt vmcnt(6)
	s_barrier
	s_waitcnt lgkmcnt(0)
	v_mfma_f32_16x16x32_bf16 v[44:47], v[198:201], v[166:169], v[44:47]
	v_mfma_f32_16x16x32_bf16 v[40:43], v[210:213], v[166:169], v[40:43]
	v_mfma_f32_16x16x32_bf16 v[28:31], v[198:201], v[174:177], v[28:31]
	v_mfma_f32_16x16x32_bf16 v[24:27], v[210:213], v[174:177], v[24:27]
	v_mfma_f32_16x16x32_bf16 v[12:15], v[198:201], v[182:185], v[12:15]
	v_mfma_f32_16x16x32_bf16 v[8:11], v[210:213], v[182:185], v[8:11]
	v_mfma_f32_16x16x32_bf16 v[4:7], v[198:201], v[190:193], v[4:7]
	v_mfma_f32_16x16x32_bf16 v[0:3], v[210:213], v[190:193], v[0:3]
	v_mfma_f32_16x16x32_bf16 v[44:47], v[202:205], v[170:173], v[44:47]
	v_mfma_f32_16x16x32_bf16 v[40:43], v[214:217], v[170:173], v[40:43]
	v_mfma_f32_16x16x32_bf16 v[28:31], v[202:205], v[178:181], v[28:31]
	v_mfma_f32_16x16x32_bf16 v[24:27], v[214:217], v[178:181], v[24:27]
	v_mfma_f32_16x16x32_bf16 v[12:15], v[202:205], v[186:189], v[12:15]
	v_mfma_f32_16x16x32_bf16 v[8:11], v[214:217], v[186:189], v[8:11]
	v_mfma_f32_16x16x32_bf16 v[4:7], v[202:205], v[194:197], v[4:7]
	v_mfma_f32_16x16x32_bf16 v[0:3], v[214:217], v[194:197], v[0:3]
	s_add_i32 s44, s44, 2
	s_add_u32 s42, s42, 0x100
	s_addc_u32 s43, s43, 0
	s_cmp_gt_u32 s44, 53
	s_mov_b64 s[14:15], s[16:17]
	s_barrier
	s_cbranch_scc0 .LBB0_974
	v_mov_b32_e32 v150, v145
	v_mov_b32_e32 v151, v144
	s_lshl_b32 s14, s34, 8
	s_add_i32 s14, s14, s29
	v_add_u32_e32 v150, s14, v150
	s_lshl_b32 s14, s41, 8
	s_or_b32 s14, s14, s30
	v_lshl_add_u32 v152, v151, 3, s14
	v_ashrrev_i32_e32 v151, 31, v150
	v_lshlrev_b64 v[150:151], 12, v[150:151]
	v_ashrrev_i32_e32 v153, 31, v152
	v_lshl_add_u64 v[150:151], s[10:11], 0, v[150:151]
	v_lshl_add_u64 v[150:151], v[152:153], 1, v[150:151]
	v_cvt_pk_bf16_f32 v108, v108, v109
	v_cvt_pk_bf16_f32 v109, v110, v111
	v_cvt_pk_bf16_f32 v110, v104, v105
	v_cvt_pk_bf16_f32 v111, v106, v107
	s_mov_b64 s[14:15], 0x10000
	global_store_dwordx4 v[150:151], v[108:111], off offset:256
	v_cvt_pk_bf16_f32 v92, v92, v93
	v_cvt_pk_bf16_f32 v93, v94, v95
	v_lshl_add_u64 v[108:109], v[150:151], 0, s[14:15]
	s_mov_b32 s14, 0x10000
	v_add_co_u32_e32 v110, vcc, s14, v150
	v_cvt_pk_bf16_f32 v94, v88, v89
	v_cvt_pk_bf16_f32 v95, v90, v91
	s_mov_b64 s[14:15], 0x20000
	v_addc_co_u32_e32 v111, vcc, 0, v151, vcc
	global_store_dwordx4 v[108:109], v[92:95], off offset:256
	v_cvt_pk_bf16_f32 v76, v76, v77
	v_cvt_pk_bf16_f32 v77, v78, v79
	v_lshl_add_u64 v[92:93], v[150:151], 0, s[14:15]
	s_mov_b32 s14, 0x20000
	v_add_co_u32_e32 v94, vcc, s14, v150
	v_cvt_pk_bf16_f32 v78, v72, v73
	v_cvt_pk_bf16_f32 v79, v74, v75
	s_mov_b64 s[14:15], 0x30000
	v_addc_co_u32_e32 v95, vcc, 0, v151, vcc
	global_store_dwordx4 v[92:93], v[76:79], off offset:256
	v_cvt_pk_bf16_f32 v68, v68, v69
	v_cvt_pk_bf16_f32 v69, v70, v71
	v_lshl_add_u64 v[76:77], v[150:151], 0, s[14:15]
	s_mov_b32 s14, 0x30000
	v_add_co_u32_e32 v78, vcc, s14, v150
	s_mov_b64 s[14:15], 0x80000
	s_nop 0
	v_addc_co_u32_e32 v79, vcc, 0, v151, vcc
	v_cvt_pk_bf16_f32 v70, v64, v65
	v_lshl_add_u64 v[64:65], v[150:151], 0, s[14:15]
	s_mov_b32 s14, 0x80000
	v_cvt_pk_bf16_f32 v60, v60, v61
	v_cvt_pk_bf16_f32 v61, v62, v63
	v_cvt_pk_bf16_f32 v62, v56, v57
	v_add_co_u32_e32 v56, vcc, s14, v150
	v_cvt_pk_bf16_f32 v44, v44, v45
	v_cvt_pk_bf16_f32 v45, v46, v47
	v_cvt_pk_bf16_f32 v46, v40, v41
	v_cvt_pk_bf16_f32 v47, v42, v43
	s_mov_b64 s[14:15], 0x90000
	v_addc_co_u32_e32 v57, vcc, 0, v151, vcc
	global_store_dwordx4 v[64:65], v[44:47], off offset:256
	v_cvt_pk_bf16_f32 v28, v28, v29
	v_cvt_pk_bf16_f32 v29, v30, v31
	v_lshl_add_u64 v[44:45], v[150:151], 0, s[14:15]
	s_mov_b32 s14, 0x90000
	v_add_co_u32_e32 v46, vcc, s14, v150
	v_cvt_pk_bf16_f32 v30, v24, v25
	s_nop 0
	v_addc_co_u32_e32 v47, vcc, 0, v151, vcc
	v_cvt_pk_bf16_f32 v31, v26, v27
	global_store_dwordx4 v[44:45], v[28:31], off offset:256
	s_mov_b64 s[14:15], 0xa0000
	v_cvt_pk_bf16_f32 v12, v12, v13
	v_add_co_u32_e32 v30, vcc, s37, v150
	v_lshl_add_u64 v[28:29], v[150:151], 0, s[14:15]
	s_nop 0
	v_addc_co_u32_e32 v31, vcc, 0, v151, vcc
	v_cvt_pk_bf16_f32 v13, v14, v15
	v_cvt_pk_bf16_f32 v14, v8, v9
	v_cvt_pk_bf16_f32 v15, v10, v11
	global_store_dwordx4 v[28:29], v[12:15], off offset:256
	v_cvt_pk_bf16_f32 v124, v124, v125
	v_cvt_pk_bf16_f32 v125, v126, v127
	v_add_co_u32_e32 v14, vcc, s38, v150
	v_cvt_pk_bf16_f32 v126, v120, v121
	s_nop 0
	v_addc_co_u32_e32 v15, vcc, 0, v151, vcc
	v_cvt_pk_bf16_f32 v127, v122, v123
	v_cvt_pk_bf16_f32 v104, v116, v117
	v_cvt_pk_bf16_f32 v105, v118, v119
	v_cvt_pk_bf16_f32 v106, v112, v113
	v_cvt_pk_bf16_f32 v107, v114, v115
	v_cvt_pk_bf16_f32 v88, v100, v101
	v_cvt_pk_bf16_f32 v89, v102, v103
	v_cvt_pk_bf16_f32 v90, v96, v97
	v_cvt_pk_bf16_f32 v91, v98, v99
	v_cvt_pk_bf16_f32 v72, v84, v85
	v_cvt_pk_bf16_f32 v73, v86, v87
	v_cvt_pk_bf16_f32 v74, v80, v81
	v_cvt_pk_bf16_f32 v75, v82, v83
	v_cvt_pk_bf16_f32 v71, v66, v67
	v_cvt_pk_bf16_f32 v63, v58, v59
	v_cvt_pk_bf16_f32 v40, v52, v53
	v_cvt_pk_bf16_f32 v41, v54, v55
	v_cvt_pk_bf16_f32 v42, v48, v49
	v_cvt_pk_bf16_f32 v43, v50, v51
	v_cvt_pk_bf16_f32 v24, v36, v37
	v_cvt_pk_bf16_f32 v25, v38, v39
	v_cvt_pk_bf16_f32 v26, v32, v33
	v_cvt_pk_bf16_f32 v27, v34, v35
	v_lshl_add_u64 v[12:13], v[150:151], 0, s[12:13]
	v_cvt_pk_bf16_f32 v8, v20, v21
	v_cvt_pk_bf16_f32 v9, v22, v23
	v_cvt_pk_bf16_f32 v10, v16, v17
	v_cvt_pk_bf16_f32 v11, v18, v19
	v_cvt_pk_bf16_f32 v4, v4, v5
	v_cvt_pk_bf16_f32 v5, v6, v7
	v_cvt_pk_bf16_f32 v6, v0, v1
	v_cvt_pk_bf16_f32 v7, v2, v3
	s_and_b64 vcc, exec, s[0:1]
	s_mov_b32 s41, s39
	s_mov_b32 s34, s40
	s_mov_b64 s[16:17], s[4:5]
	s_mov_b64 s[14:15], s[2:3]
	global_store_dwordx4 v[150:151], v[124:127], off
	global_store_dwordx4 v[110:111], v[104:107], off
	global_store_dwordx4 v[94:95], v[88:91], off
	global_store_dwordx4 v[78:79], v[72:75], off
	global_store_dwordx4 v[76:77], v[68:71], off offset:256
	global_store_dwordx4 v[56:57], v[60:63], off
	global_store_dwordx4 v[46:47], v[40:43], off
	global_store_dwordx4 v[30:31], v[24:27], off
	global_store_dwordx4 v[14:15], v[8:11], off
	global_store_dwordx4 v[12:13], v[4:7], off offset:256
	s_cbranch_vccz .LBB0_963
	s_waitcnt vmcnt(0)
	s_cmpk_gt_u32 s22, 0xff
	s_cbranch_scc1 .LBB0_978
	s_barrier

.LBB0_1200:
	s_waitcnt lgkmcnt(0)
	s_add_u32 s30, s28, 0xfff80080
	s_addc_u32 s31, s29, -1
	s_cmp_eq_u32 s56, 28
	s_cselect_b32 s35, s4, s31
	s_cselect_b32 s34, s7, s30
	s_cselect_b32 s31, s21, s55
	s_cselect_b32 s30, s23, s54
	v_lshl_add_u64 v[200:201], s[28:29], 0, v[136:137]
	s_add_i32 m0, s17, 0xc000
	ds_read_b128 v[168:171], v152
	ds_read_b128 v[172:175], v152 offset:1024
	ds_read_b128 v[176:179], v152 offset:2048
	ds_read_b128 v[180:183], v152 offset:3072
	ds_read_b128 v[184:187], v152 offset:4096
	ds_read_b128 v[188:191], v152 offset:5120
	ds_read_b128 v[192:195], v152 offset:6144
	ds_read_b128 v[196:199], v152 offset:7168
	global_load_lds_dwordx4 v[200:201], off
	v_lshl_add_u64 v[200:201], s[28:29], 0, v[138:139]
	s_add_i32 m0, s17, 0xe000
	s_nop 0
	global_load_lds_dwordx4 v[200:201], off
	s_waitcnt lgkmcnt(8)
	s_barrier
	s_waitcnt lgkmcnt(0)
	s_waitcnt lgkmcnt(0)
	v_mfma_f32_16x16x32_bf16 v[124:127], v[144:147], v[168:171], v[124:127]
	v_mfma_f32_16x16x32_bf16 v[120:123], v[160:163], v[168:171], v[120:123]
	v_mfma_f32_16x16x32_bf16 v[116:119], v[144:147], v[176:179], v[116:119]
	v_mfma_f32_16x16x32_bf16 v[112:115], v[160:163], v[176:179], v[112:115]
	v_mfma_f32_16x16x32_bf16 v[100:103], v[144:147], v[184:187], v[100:103]
	v_mfma_f32_16x16x32_bf16 v[96:99], v[160:163], v[184:187], v[96:99]
	v_mfma_f32_16x16x32_bf16 v[84:87], v[144:147], v[192:195], v[84:87]
	v_mfma_f32_16x16x32_bf16 v[80:83], v[160:163], v[192:195], v[80:83]
	v_mfma_f32_16x16x32_bf16 v[124:127], v[156:159], v[172:175], v[124:127]
	v_mfma_f32_16x16x32_bf16 v[120:123], v[164:167], v[172:175], v[120:123]
	v_mfma_f32_16x16x32_bf16 v[116:119], v[156:159], v[180:183], v[116:119]
	v_mfma_f32_16x16x32_bf16 v[112:115], v[164:167], v[180:183], v[112:115]
	v_mfma_f32_16x16x32_bf16 v[100:103], v[156:159], v[188:191], v[100:103]
	v_mfma_f32_16x16x32_bf16 v[96:99], v[164:167], v[188:191], v[96:99]
	v_mfma_f32_16x16x32_bf16 v[84:87], v[156:159], v[196:199], v[84:87]
	v_mfma_f32_16x16x32_bf16 v[80:83], v[164:167], v[196:199], v[80:83]
	s_barrier
	s_add_i32 s57, s45, s33
	v_lshl_add_u64 v[218:219], s[30:31], 0, v[130:131]
	s_mov_b32 m0, s57
	ds_read_b128 v[200:203], v153
	ds_read_b128 v[204:207], v153 offset:1024
	ds_read_b128 v[210:213], v153 offset:2048
	ds_read_b128 v[214:217], v153 offset:3072
	global_load_lds_dwordx4 v[218:219], off
	v_lshl_add_u64 v[220:221], s[30:31], 0, v[134:135]
	s_add_i32 m0, s57, 0x2000
	s_nop 0
	global_load_lds_dwordx4 v[220:221], off
	s_barrier
	s_waitcnt lgkmcnt(0)
	s_waitcnt lgkmcnt(0)
	v_mfma_f32_16x16x32_bf16 v[108:111], v[200:203], v[168:171], v[108:111]
	v_mfma_f32_16x16x32_bf16 v[104:107], v[210:213], v[168:171], v[104:107]
	v_mfma_f32_16x16x32_bf16 v[92:95], v[200:203], v[176:179], v[92:95]
	v_mfma_f32_16x16x32_bf16 v[88:91], v[210:213], v[176:179], v[88:91]
	v_mfma_f32_16x16x32_bf16 v[76:79], v[200:203], v[184:187], v[76:79]
	v_mfma_f32_16x16x32_bf16 v[72:75], v[210:213], v[184:187], v[72:75]
	v_mfma_f32_16x16x32_bf16 v[68:71], v[200:203], v[192:195], v[68:71]
	v_mfma_f32_16x16x32_bf16 v[64:67], v[210:213], v[192:195], v[64:67]
	v_mfma_f32_16x16x32_bf16 v[108:111], v[204:207], v[172:175], v[108:111]
	v_mfma_f32_16x16x32_bf16 v[104:107], v[214:217], v[172:175], v[104:107]
	v_mfma_f32_16x16x32_bf16 v[92:95], v[204:207], v[180:183], v[92:95]
	v_mfma_f32_16x16x32_bf16 v[88:91], v[214:217], v[180:183], v[88:91]
	v_mfma_f32_16x16x32_bf16 v[76:79], v[204:207], v[188:191], v[76:79]
	v_mfma_f32_16x16x32_bf16 v[72:75], v[214:217], v[188:191], v[72:75]
	v_mfma_f32_16x16x32_bf16 v[68:71], v[204:207], v[196:199], v[68:71]
	v_mfma_f32_16x16x32_bf16 v[64:67], v[214:217], v[196:199], v[64:67]
	s_mov_b32 m0, s17
	v_lshl_add_u64 v[222:223], s[34:35], 0, v[128:129]
	s_barrier
	ds_read_b128 v[168:171], v152 offset:16384
	ds_read_b128 v[172:175], v152 offset:17408
	ds_read_b128 v[176:179], v152 offset:18432
	ds_read_b128 v[180:183], v152 offset:19456
	ds_read_b128 v[184:187], v152 offset:20480
	ds_read_b128 v[188:191], v152 offset:21504
	ds_read_b128 v[192:195], v152 offset:22528
	ds_read_b128 v[196:199], v152 offset:23552
	global_load_lds_dwordx4 v[222:223], off
	v_lshl_add_u64 v[224:225], s[34:35], 0, v[132:133]
	s_mov_b32 m0, s38
	s_nop 0
	global_load_lds_dwordx4 v[224:225], off
	s_waitcnt vmcnt(10)
	s_barrier
	s_waitcnt lgkmcnt(0)
	s_waitcnt lgkmcnt(0)
	v_mfma_f32_16x16x32_bf16 v[60:63], v[144:147], v[168:171], v[60:63]
	v_mfma_f32_16x16x32_bf16 v[56:59], v[160:163], v[168:171], v[56:59]
	v_mfma_f32_16x16x32_bf16 v[52:55], v[144:147], v[176:179], v[52:55]
	v_mfma_f32_16x16x32_bf16 v[48:51], v[160:163], v[176:179], v[48:51]
	v_mfma_f32_16x16x32_bf16 v[36:39], v[144:147], v[184:187], v[36:39]
	v_mfma_f32_16x16x32_bf16 v[32:35], v[160:163], v[184:187], v[32:35]
	v_mfma_f32_16x16x32_bf16 v[20:23], v[144:147], v[192:195], v[20:23]
	v_mfma_f32_16x16x32_bf16 v[16:19], v[160:163], v[192:195], v[16:19]
	v_mfma_f32_16x16x32_bf16 v[60:63], v[156:159], v[172:175], v[60:63]
	v_mfma_f32_16x16x32_bf16 v[56:59], v[164:167], v[172:175], v[56:59]
	v_mfma_f32_16x16x32_bf16 v[52:55], v[156:159], v[180:183], v[52:55]
	v_mfma_f32_16x16x32_bf16 v[48:51], v[164:167], v[180:183], v[48:51]
	v_mfma_f32_16x16x32_bf16 v[36:39], v[156:159], v[188:191], v[36:39]
	v_mfma_f32_16x16x32_bf16 v[32:35], v[164:167], v[188:191], v[32:35]
	v_mfma_f32_16x16x32_bf16 v[20:23], v[156:159], v[196:199], v[20:23]
	v_mfma_f32_16x16x32_bf16 v[16:19], v[164:167], v[196:199], v[16:19]
	s_barrier
	s_add_u32 s60, s30, 0x80000
	s_addc_u32 s61, s31, 0
	s_add_i32 s57, s51, s33
	v_lshl_add_u64 v[144:145], s[60:61], 0, v[130:131]
	s_mov_b32 m0, s57
	s_nop 0
	global_load_lds_dwordx4 v[144:145], off
	v_lshl_add_u64 v[144:145], s[60:61], 0, v[134:135]
	s_add_i32 m0, s57, 0x2000
	s_nop 0
	global_load_lds_dwordx4 v[144:145], off
	s_add_i32 s57, 0, 0x18000
	v_add_u32_e32 v155, s57, v150
	ds_read_b128 v[144:147], v155
	ds_read_b128 v[156:159], v155 offset:1024
	ds_read_b128 v[160:163], v155 offset:2048
	ds_read_b128 v[164:167], v155 offset:3072
	s_waitcnt vmcnt(6)
	s_barrier
	v_mfma_f32_16x16x32_bf16 v[44:47], v[200:203], v[168:171], v[44:47]
	v_mfma_f32_16x16x32_bf16 v[40:43], v[210:213], v[168:171], v[40:43]
	v_mfma_f32_16x16x32_bf16 v[28:31], v[200:203], v[176:179], v[28:31]
	v_mfma_f32_16x16x32_bf16 v[24:27], v[210:213], v[176:179], v[24:27]
	v_mfma_f32_16x16x32_bf16 v[12:15], v[200:203], v[184:187], v[12:15]
	v_mfma_f32_16x16x32_bf16 v[8:11], v[210:213], v[184:187], v[8:11]
	v_mfma_f32_16x16x32_bf16 v[4:7], v[200:203], v[192:195], v[4:7]
	v_mfma_f32_16x16x32_bf16 v[0:3], v[210:213], v[192:195], v[0:3]
	v_mfma_f32_16x16x32_bf16 v[44:47], v[204:207], v[172:175], v[44:47]
	v_mfma_f32_16x16x32_bf16 v[40:43], v[214:217], v[172:175], v[40:43]
	v_mfma_f32_16x16x32_bf16 v[28:31], v[204:207], v[180:183], v[28:31]
	v_mfma_f32_16x16x32_bf16 v[24:27], v[214:217], v[180:183], v[24:27]
	v_mfma_f32_16x16x32_bf16 v[12:15], v[204:207], v[188:191], v[12:15]
	v_mfma_f32_16x16x32_bf16 v[8:11], v[214:217], v[188:191], v[8:11]
	v_mfma_f32_16x16x32_bf16 v[4:7], v[204:207], v[196:199], v[4:7]
	v_mfma_f32_16x16x32_bf16 v[0:3], v[214:217], v[196:199], v[0:3]
	s_barrier
	s_add_u32 s34, s34, 0x80000
	s_addc_u32 s35, s35, 0
	s_mov_b32 m0, s39
	v_lshl_add_u64 v[200:201], s[34:35], 0, v[128:129]
	ds_read_b128 v[168:171], v152 offset:32768
	ds_read_b128 v[172:175], v152 offset:33792
	ds_read_b128 v[176:179], v152 offset:34816
	ds_read_b128 v[180:183], v152 offset:35840
	ds_read_b128 v[184:187], v152 offset:36864
	ds_read_b128 v[188:191], v152 offset:37888
	ds_read_b128 v[192:195], v152 offset:38912
	ds_read_b128 v[196:199], v152 offset:39936
	global_load_lds_dwordx4 v[200:201], off
	v_lshl_add_u64 v[200:201], s[34:35], 0, v[132:133]
	s_mov_b32 m0, s40
	s_nop 0
	global_load_lds_dwordx4 v[200:201], off
	s_waitcnt lgkmcnt(8)
	s_barrier
	s_waitcnt lgkmcnt(0)
	s_waitcnt lgkmcnt(0)
	v_mfma_f32_16x16x32_bf16 v[124:127], v[144:147], v[168:171], v[124:127]
	v_mfma_f32_16x16x32_bf16 v[120:123], v[160:163], v[168:171], v[120:123]
	v_mfma_f32_16x16x32_bf16 v[116:119], v[144:147], v[176:179], v[116:119]
	v_mfma_f32_16x16x32_bf16 v[112:115], v[160:163], v[176:179], v[112:115]
	v_mfma_f32_16x16x32_bf16 v[100:103], v[144:147], v[184:187], v[100:103]
	v_mfma_f32_16x16x32_bf16 v[96:99], v[160:163], v[184:187], v[96:99]
	v_mfma_f32_16x16x32_bf16 v[84:87], v[144:147], v[192:195], v[84:87]
	v_mfma_f32_16x16x32_bf16 v[80:83], v[160:163], v[192:195], v[80:83]
	v_mfma_f32_16x16x32_bf16 v[124:127], v[156:159], v[172:175], v[124:127]
	v_mfma_f32_16x16x32_bf16 v[120:123], v[164:167], v[172:175], v[120:123]
	v_mfma_f32_16x16x32_bf16 v[116:119], v[156:159], v[180:183], v[116:119]
	v_mfma_f32_16x16x32_bf16 v[112:115], v[164:167], v[180:183], v[112:115]
	v_mfma_f32_16x16x32_bf16 v[100:103], v[156:159], v[188:191], v[100:103]
	v_mfma_f32_16x16x32_bf16 v[96:99], v[164:167], v[188:191], v[96:99]
	v_mfma_f32_16x16x32_bf16 v[84:87], v[156:159], v[196:199], v[84:87]
	v_mfma_f32_16x16x32_bf16 v[80:83], v[164:167], v[196:199], v[80:83]
	s_barrier
	s_add_i32 s34, 0, 0x1c000
	s_add_i32 s35, s57, s33
	v_add_u32_e32 v155, s34, v150
	v_lshl_add_u64 v[218:219], v[218:219], 0, s[8:9]
	s_mov_b32 m0, s35
	ds_read_b128 v[200:203], v155
	ds_read_b128 v[204:207], v155 offset:1024
	ds_read_b128 v[210:213], v155 offset:2048
	ds_read_b128 v[214:217], v155 offset:3072
	global_load_lds_dwordx4 v[218:219], off
	v_lshl_add_u64 v[218:219], v[220:221], 0, s[8:9]
	s_add_i32 m0, s35, 0x2000
	s_nop 0
	global_load_lds_dwordx4 v[218:219], off
	s_barrier
	s_waitcnt lgkmcnt(0)
	s_waitcnt lgkmcnt(0)
	v_mfma_f32_16x16x32_bf16 v[108:111], v[200:203], v[168:171], v[108:111]
	v_mfma_f32_16x16x32_bf16 v[104:107], v[210:213], v[168:171], v[104:107]
	v_mfma_f32_16x16x32_bf16 v[92:95], v[200:203], v[176:179], v[92:95]
	v_mfma_f32_16x16x32_bf16 v[88:91], v[210:213], v[176:179], v[88:91]
	v_mfma_f32_16x16x32_bf16 v[76:79], v[200:203], v[184:187], v[76:79]
	v_mfma_f32_16x16x32_bf16 v[72:75], v[210:213], v[184:187], v[72:75]
	v_mfma_f32_16x16x32_bf16 v[68:71], v[200:203], v[192:195], v[68:71]
	v_mfma_f32_16x16x32_bf16 v[64:67], v[210:213], v[192:195], v[64:67]
	v_mfma_f32_16x16x32_bf16 v[108:111], v[204:207], v[172:175], v[108:111]
	v_mfma_f32_16x16x32_bf16 v[104:107], v[214:217], v[172:175], v[104:107]
	v_mfma_f32_16x16x32_bf16 v[92:95], v[204:207], v[180:183], v[92:95]
	v_mfma_f32_16x16x32_bf16 v[88:91], v[214:217], v[180:183], v[88:91]
	v_mfma_f32_16x16x32_bf16 v[76:79], v[204:207], v[188:191], v[76:79]
	v_mfma_f32_16x16x32_bf16 v[72:75], v[214:217], v[188:191], v[72:75]
	v_mfma_f32_16x16x32_bf16 v[68:71], v[204:207], v[196:199], v[68:71]
	v_mfma_f32_16x16x32_bf16 v[64:67], v[214:217], v[196:199], v[64:67]
	s_mov_b32 m0, s43
	v_lshl_add_u64 v[218:219], v[222:223], 0, s[8:9]
	s_barrier
	ds_read_b128 v[168:171], v152 offset:49152
	ds_read_b128 v[172:175], v152 offset:50176
	ds_read_b128 v[176:179], v152 offset:51200
	ds_read_b128 v[180:183], v152 offset:52224
	ds_read_b128 v[184:187], v152 offset:53248
	ds_read_b128 v[188:191], v152 offset:54272
	ds_read_b128 v[192:195], v152 offset:55296
	ds_read_b128 v[196:199], v152 offset:56320
	global_load_lds_dwordx4 v[218:219], off
	v_lshl_add_u64 v[218:219], v[224:225], 0, s[8:9]
	s_mov_b32 m0, s44
	s_nop 0
	global_load_lds_dwordx4 v[218:219], off
	s_waitcnt vmcnt(10)
	s_barrier
	s_waitcnt lgkmcnt(0)
	s_waitcnt lgkmcnt(0)
	v_mfma_f32_16x16x32_bf16 v[60:63], v[144:147], v[168:171], v[60:63]
	v_mfma_f32_16x16x32_bf16 v[56:59], v[160:163], v[168:171], v[56:59]
	v_mfma_f32_16x16x32_bf16 v[52:55], v[144:147], v[176:179], v[52:55]
	v_mfma_f32_16x16x32_bf16 v[48:51], v[160:163], v[176:179], v[48:51]
	v_mfma_f32_16x16x32_bf16 v[36:39], v[144:147], v[184:187], v[36:39]
	v_mfma_f32_16x16x32_bf16 v[32:35], v[160:163], v[184:187], v[32:35]
	v_mfma_f32_16x16x32_bf16 v[20:23], v[144:147], v[192:195], v[20:23]
	v_mfma_f32_16x16x32_bf16 v[16:19], v[160:163], v[192:195], v[16:19]
	v_mfma_f32_16x16x32_bf16 v[60:63], v[156:159], v[172:175], v[60:63]
	v_mfma_f32_16x16x32_bf16 v[56:59], v[164:167], v[172:175], v[56:59]
	v_mfma_f32_16x16x32_bf16 v[52:55], v[156:159], v[180:183], v[52:55]
	v_mfma_f32_16x16x32_bf16 v[48:51], v[164:167], v[180:183], v[48:51]
	v_mfma_f32_16x16x32_bf16 v[36:39], v[156:159], v[188:191], v[36:39]
	v_mfma_f32_16x16x32_bf16 v[32:35], v[164:167], v[188:191], v[32:35]
	v_mfma_f32_16x16x32_bf16 v[20:23], v[156:159], v[196:199], v[20:23]
	v_mfma_f32_16x16x32_bf16 v[16:19], v[164:167], v[196:199], v[16:19]
	s_barrier
	s_add_u32 s30, s30, 0x80080
	s_addc_u32 s31, s31, 0
	s_add_i32 s34, s34, s33
	v_lshl_add_u64 v[144:145], s[30:31], 0, v[130:131]
	s_mov_b32 m0, s34
	s_nop 0
	global_load_lds_dwordx4 v[144:145], off
	v_lshl_add_u64 v[144:145], s[30:31], 0, v[134:135]
	s_add_i32 m0, s34, 0x2000
	s_nop 0
	global_load_lds_dwordx4 v[144:145], off
	ds_read_b128 v[144:147], v151
	ds_read_b128 v[156:159], v151 offset:1024
	ds_read_b128 v[160:163], v151 offset:2048
	ds_read_b128 v[164:167], v151 offset:3072
	s_waitcnt vmcnt(6)
	s_barrier
	s_waitcnt lgkmcnt(0)
	v_mfma_f32_16x16x32_bf16 v[44:47], v[200:203], v[168:171], v[44:47]
	v_mfma_f32_16x16x32_bf16 v[40:43], v[210:213], v[168:171], v[40:43]
	v_mfma_f32_16x16x32_bf16 v[28:31], v[200:203], v[176:179], v[28:31]
	v_mfma_f32_16x16x32_bf16 v[24:27], v[210:213], v[176:179], v[24:27]
	v_mfma_f32_16x16x32_bf16 v[12:15], v[200:203], v[184:187], v[12:15]
	v_mfma_f32_16x16x32_bf16 v[8:11], v[210:213], v[184:187], v[8:11]
	v_mfma_f32_16x16x32_bf16 v[4:7], v[200:203], v[192:195], v[4:7]
	v_mfma_f32_16x16x32_bf16 v[0:3], v[210:213], v[192:195], v[0:3]
	v_mfma_f32_16x16x32_bf16 v[44:47], v[204:207], v[172:175], v[44:47]
	v_mfma_f32_16x16x32_bf16 v[40:43], v[214:217], v[172:175], v[40:43]
	v_mfma_f32_16x16x32_bf16 v[28:31], v[204:207], v[180:183], v[28:31]
	v_mfma_f32_16x16x32_bf16 v[24:27], v[214:217], v[180:183], v[24:27]
	v_mfma_f32_16x16x32_bf16 v[12:15], v[204:207], v[188:191], v[12:15]
	v_mfma_f32_16x16x32_bf16 v[8:11], v[214:217], v[188:191], v[8:11]
	v_mfma_f32_16x16x32_bf16 v[4:7], v[204:207], v[196:199], v[4:7]
	v_mfma_f32_16x16x32_bf16 v[0:3], v[214:217], v[196:199], v[0:3]
	s_add_i32 s56, s56, 2
	s_add_u32 s28, s28, 0x100
	s_addc_u32 s29, s29, 0
	s_add_u32 s54, s54, 0x100
	s_addc_u32 s55, s55, 0
	s_cmp_gt_u32 s56, 29
	s_barrier
	s_cbranch_scc0 .LBB0_1200
	v_mov_b32_e32 v155, v148
	v_mov_b32_e32 v156, v149
	s_cmp_gt_i32 s6, 7
	s_mov_b64 s[28:29], -1
	s_cbranch_scc0 .LBB0_1231
	s_cmp_gt_u32 s6, 15
	s_cbranch_scc0 .LBB0_1212
	s_cmp_gt_u32 s6, 23
	s_cbranch_scc0 .LBB0_1209
	s_lshl_b32 s4, s16, 8
	s_add_i32 s4, s4, s41
	v_lshl_add_u32 v144, v156, 3, s42
	v_add_u32_e32 v157, s4, v155
	v_ashrrev_i32_e32 v145, 31, v144
	v_mad_i64_i32 v[146:147], s[28:29], v157, s52, 0
	s_cmp_gt_u32 s6, 25
	s_mov_b64 s[28:29], -1
	v_lshl_add_u64 v[146:147], s[14:15], 0, v[146:147]
	v_lshlrev_b64 v[144:145], 1, v[144:145]
	v_add_u32_e32 v163, 16, v157
	v_add_u32_e32 v162, 32, v157
	v_add_u32_e32 v161, 48, v157
	v_add_u32_e32 v160, 0x80, v157
	v_add_u32_e32 v159, 0x90, v157
	v_add_u32_e32 v158, 0xa0, v157
	v_add_u32_e32 v157, 0xb0, v157
	s_cbranch_scc0 .LBB0_1206
	s_lshl_b32 s4, s6, 9
	v_lshl_add_u64 v[168:169], v[146:147], 0, s[4:5]
	v_cvt_pk_bf16_f32 v164, v124, v125
	v_cvt_pk_bf16_f32 v165, v126, v127
	v_cvt_pk_bf16_f32 v166, v120, v121
	v_cvt_pk_bf16_f32 v167, v122, v123
	v_lshl_add_u64 v[168:169], v[168:169], 0, v[144:145]
	global_store_dwordx4 v[168:169], v[164:167], off
	s_nop 1
	v_cvt_pk_bf16_f32 v164, v108, v109
	v_cvt_pk_bf16_f32 v165, v110, v111
	v_cvt_pk_bf16_f32 v166, v104, v105
	v_cvt_pk_bf16_f32 v167, v106, v107
	global_store_dwordx4 v[168:169], v[164:167], off offset:256
	v_mov_b64_e32 v[168:169], s[14:15]
	v_mad_i64_i32 v[170:171], s[28:29], v163, s52, v[168:169]
	v_lshl_add_u64 v[170:171], v[170:171], 0, s[4:5]
	v_cvt_pk_bf16_f32 v164, v116, v117
	v_cvt_pk_bf16_f32 v165, v118, v119
	v_cvt_pk_bf16_f32 v166, v112, v113
	v_cvt_pk_bf16_f32 v167, v114, v115
	v_lshl_add_u64 v[170:171], v[170:171], 0, v[144:145]
	global_store_dwordx4 v[170:171], v[164:167], off
	s_nop 1
	v_cvt_pk_bf16_f32 v164, v92, v93
	v_cvt_pk_bf16_f32 v165, v94, v95
	v_cvt_pk_bf16_f32 v166, v88, v89
	v_cvt_pk_bf16_f32 v167, v90, v91
	global_store_dwordx4 v[170:171], v[164:167], off offset:256
	v_mad_i64_i32 v[170:171], s[28:29], v162, s52, v[168:169]
	v_lshl_add_u64 v[170:171], v[170:171], 0, s[4:5]
	v_cvt_pk_bf16_f32 v164, v100, v101
	v_cvt_pk_bf16_f32 v165, v102, v103
	v_cvt_pk_bf16_f32 v166, v96, v97
	v_cvt_pk_bf16_f32 v167, v98, v99
	v_lshl_add_u64 v[170:171], v[170:171], 0, v[144:145]
	global_store_dwordx4 v[170:171], v[164:167], off
	s_nop 1
	v_cvt_pk_bf16_f32 v164, v76, v77
	v_cvt_pk_bf16_f32 v165, v78, v79
	v_cvt_pk_bf16_f32 v166, v72, v73
	v_cvt_pk_bf16_f32 v167, v74, v75
	global_store_dwordx4 v[170:171], v[164:167], off offset:256
	v_mad_i64_i32 v[170:171], s[28:29], v161, s52, v[168:169]
	v_lshl_add_u64 v[170:171], v[170:171], 0, s[4:5]
	v_cvt_pk_bf16_f32 v164, v84, v85
	v_cvt_pk_bf16_f32 v165, v86, v87
	v_cvt_pk_bf16_f32 v166, v80, v81
	v_cvt_pk_bf16_f32 v167, v82, v83
	v_lshl_add_u64 v[170:171], v[170:171], 0, v[144:145]
	global_store_dwordx4 v[170:171], v[164:167], off
	s_nop 1
	v_cvt_pk_bf16_f32 v164, v68, v69
	v_cvt_pk_bf16_f32 v165, v70, v71
	v_cvt_pk_bf16_f32 v166, v64, v65
	v_cvt_pk_bf16_f32 v167, v66, v67
	global_store_dwordx4 v[170:171], v[164:167], off offset:256
	v_mad_i64_i32 v[170:171], s[28:29], v160, s52, v[168:169]
	v_lshl_add_u64 v[170:171], v[170:171], 0, s[4:5]
	v_cvt_pk_bf16_f32 v164, v60, v61
	v_cvt_pk_bf16_f32 v165, v62, v63
	v_cvt_pk_bf16_f32 v166, v56, v57
	v_cvt_pk_bf16_f32 v167, v58, v59
	v_lshl_add_u64 v[170:171], v[170:171], 0, v[144:145]
	global_store_dwordx4 v[170:171], v[164:167], off
	s_nop 1
	v_cvt_pk_bf16_f32 v164, v44, v45
	v_cvt_pk_bf16_f32 v165, v46, v47
	v_cvt_pk_bf16_f32 v166, v40, v41
	v_cvt_pk_bf16_f32 v167, v42, v43
	global_store_dwordx4 v[170:171], v[164:167], off offset:256
	v_mad_i64_i32 v[170:171], s[28:29], v159, s52, v[168:169]
	v_lshl_add_u64 v[170:171], v[170:171], 0, s[4:5]
	v_cvt_pk_bf16_f32 v164, v52, v53
	v_cvt_pk_bf16_f32 v165, v54, v55
	v_cvt_pk_bf16_f32 v166, v48, v49
	v_cvt_pk_bf16_f32 v167, v50, v51
	v_lshl_add_u64 v[170:171], v[170:171], 0, v[144:145]
	global_store_dwordx4 v[170:171], v[164:167], off
	s_nop 1
	v_cvt_pk_bf16_f32 v164, v28, v29
	v_cvt_pk_bf16_f32 v165, v30, v31
	v_cvt_pk_bf16_f32 v166, v24, v25
	v_cvt_pk_bf16_f32 v167, v26, v27
	global_store_dwordx4 v[170:171], v[164:167], off offset:256
	v_mad_i64_i32 v[170:171], s[28:29], v158, s52, v[168:169]
	v_lshl_add_u64 v[170:171], v[170:171], 0, s[4:5]
	v_cvt_pk_bf16_f32 v164, v36, v37
	v_cvt_pk_bf16_f32 v165, v38, v39
	v_cvt_pk_bf16_f32 v166, v32, v33
	v_cvt_pk_bf16_f32 v167, v34, v35
	v_lshl_add_u64 v[170:171], v[170:171], 0, v[144:145]
	v_mad_i64_i32 v[168:169], s[28:29], v157, s52, v[168:169]
	global_store_dwordx4 v[170:171], v[164:167], off
	v_lshl_add_u64 v[168:169], v[168:169], 0, s[4:5]
	v_lshl_add_u64 v[168:169], v[168:169], 0, v[144:145]
	v_cvt_pk_bf16_f32 v164, v12, v13
	v_cvt_pk_bf16_f32 v165, v14, v15
	v_cvt_pk_bf16_f32 v166, v8, v9
	v_cvt_pk_bf16_f32 v167, v10, v11
	global_store_dwordx4 v[170:171], v[164:167], off offset:256
	s_mov_b64 s[28:29], 0
	s_nop 0
	v_cvt_pk_bf16_f32 v164, v20, v21
	v_cvt_pk_bf16_f32 v165, v22, v23
	v_cvt_pk_bf16_f32 v166, v16, v17
	v_cvt_pk_bf16_f32 v167, v18, v19
	global_store_dwordx4 v[168:169], v[164:167], off
	s_nop 1
	v_cvt_pk_bf16_f32 v164, v4, v5
	v_cvt_pk_bf16_f32 v165, v6, v7
	v_cvt_pk_bf16_f32 v166, v0, v1
	v_cvt_pk_bf16_f32 v167, v2, v3
	global_store_dwordx4 v[168:169], v[164:167], off offset:256

.LBB0_1402:
	s_add_u32 s34, s30, 0x100
	s_addc_u32 s35, s31, 0
	s_cmp_eq_u32 s69, 36
	s_cselect_b32 s39, s5, s35
	s_cselect_b32 s38, s4, s34
	s_cselect_b32 s37, s7, s68
	s_cselect_b32 s36, s6, s67
	v_lshl_add_u64 v[198:199], s[30:31], 0, v[136:137]
	s_add_i32 m0, s41, 0xc000
	ds_read_b128 v[166:169], v148
	ds_read_b128 v[170:173], v148 offset:1024
	ds_read_b128 v[174:177], v148 offset:2048
	ds_read_b128 v[178:181], v148 offset:3072
	ds_read_b128 v[182:185], v148 offset:4096
	ds_read_b128 v[186:189], v148 offset:5120
	ds_read_b128 v[190:193], v148 offset:6144
	ds_read_b128 v[194:197], v148 offset:7168
	global_load_lds_dwordx4 v[198:199], off
	v_lshl_add_u64 v[198:199], s[30:31], 0, v[138:139]
	s_add_i32 m0, s41, 0xe000
	s_nop 0
	global_load_lds_dwordx4 v[198:199], off
	s_waitcnt lgkmcnt(8)
	s_barrier
	s_waitcnt lgkmcnt(0)
	s_waitcnt lgkmcnt(0)
	v_mfma_f32_16x16x32_bf16 v[124:127], v[150:153], v[166:169], v[124:127]
	v_mfma_f32_16x16x32_bf16 v[120:123], v[158:161], v[166:169], v[120:123]
	v_mfma_f32_16x16x32_bf16 v[116:119], v[150:153], v[174:177], v[116:119]
	v_mfma_f32_16x16x32_bf16 v[112:115], v[158:161], v[174:177], v[112:115]
	v_mfma_f32_16x16x32_bf16 v[100:103], v[150:153], v[182:185], v[100:103]
	v_mfma_f32_16x16x32_bf16 v[96:99], v[158:161], v[182:185], v[96:99]
	v_mfma_f32_16x16x32_bf16 v[84:87], v[150:153], v[190:193], v[84:87]
	v_mfma_f32_16x16x32_bf16 v[80:83], v[158:161], v[190:193], v[80:83]
	v_mfma_f32_16x16x32_bf16 v[124:127], v[154:157], v[170:173], v[124:127]
	v_mfma_f32_16x16x32_bf16 v[120:123], v[162:165], v[170:173], v[120:123]
	v_mfma_f32_16x16x32_bf16 v[116:119], v[154:157], v[178:181], v[116:119]
	v_mfma_f32_16x16x32_bf16 v[112:115], v[162:165], v[178:181], v[112:115]
	v_mfma_f32_16x16x32_bf16 v[100:103], v[154:157], v[186:189], v[100:103]
	v_mfma_f32_16x16x32_bf16 v[96:99], v[162:165], v[186:189], v[96:99]
	v_mfma_f32_16x16x32_bf16 v[84:87], v[154:157], v[194:197], v[84:87]
	v_mfma_f32_16x16x32_bf16 v[80:83], v[162:165], v[194:197], v[80:83]
	s_barrier
	s_add_i32 s30, s54, s40
	v_lshl_add_u64 v[206:207], s[36:37], 0, v[130:131]
	s_mov_b32 m0, s30
	ds_read_b128 v[198:201], v149
	ds_read_b128 v[202:205], v149 offset:1024
	ds_read_b128 v[210:213], v149 offset:2048
	ds_read_b128 v[214:217], v149 offset:3072
	global_load_lds_dwordx4 v[206:207], off
	v_lshl_add_u64 v[218:219], s[36:37], 0, v[134:135]
	s_add_i32 m0, s30, 0x2000
	s_nop 0
	global_load_lds_dwordx4 v[218:219], off
	s_barrier
	s_waitcnt lgkmcnt(0)
	s_waitcnt lgkmcnt(0)
	v_mfma_f32_16x16x32_bf16 v[108:111], v[198:201], v[166:169], v[108:111]
	v_mfma_f32_16x16x32_bf16 v[104:107], v[210:213], v[166:169], v[104:107]
	v_mfma_f32_16x16x32_bf16 v[92:95], v[198:201], v[174:177], v[92:95]
	v_mfma_f32_16x16x32_bf16 v[88:91], v[210:213], v[174:177], v[88:91]
	v_mfma_f32_16x16x32_bf16 v[76:79], v[198:201], v[182:185], v[76:79]
	v_mfma_f32_16x16x32_bf16 v[72:75], v[210:213], v[182:185], v[72:75]
	v_mfma_f32_16x16x32_bf16 v[68:71], v[198:201], v[190:193], v[68:71]
	v_mfma_f32_16x16x32_bf16 v[64:67], v[210:213], v[190:193], v[64:67]
	v_mfma_f32_16x16x32_bf16 v[108:111], v[202:205], v[170:173], v[108:111]
	v_mfma_f32_16x16x32_bf16 v[104:107], v[214:217], v[170:173], v[104:107]
	v_mfma_f32_16x16x32_bf16 v[92:95], v[202:205], v[178:181], v[92:95]
	v_mfma_f32_16x16x32_bf16 v[88:91], v[214:217], v[178:181], v[88:91]
	v_mfma_f32_16x16x32_bf16 v[76:79], v[202:205], v[186:189], v[76:79]
	v_mfma_f32_16x16x32_bf16 v[72:75], v[214:217], v[186:189], v[72:75]
	v_mfma_f32_16x16x32_bf16 v[68:71], v[202:205], v[194:197], v[68:71]
	v_mfma_f32_16x16x32_bf16 v[64:67], v[214:217], v[194:197], v[64:67]
	s_mov_b32 m0, s41
	v_lshl_add_u64 v[220:221], s[38:39], 0, v[128:129]
	s_barrier
	ds_read_b128 v[166:169], v148 offset:16384
	ds_read_b128 v[170:173], v148 offset:17408
	ds_read_b128 v[174:177], v148 offset:18432
	ds_read_b128 v[178:181], v148 offset:19456
	ds_read_b128 v[182:185], v148 offset:20480
	ds_read_b128 v[186:189], v148 offset:21504
	ds_read_b128 v[190:193], v148 offset:22528
	ds_read_b128 v[194:197], v148 offset:23552
	global_load_lds_dwordx4 v[220:221], off
	v_lshl_add_u64 v[222:223], s[38:39], 0, v[132:133]
	s_mov_b32 m0, s42
	s_nop 0
	global_load_lds_dwordx4 v[222:223], off
	s_waitcnt vmcnt(10)
	s_barrier
	s_waitcnt lgkmcnt(0)
	s_waitcnt lgkmcnt(0)
	v_mfma_f32_16x16x32_bf16 v[60:63], v[150:153], v[166:169], v[60:63]
	v_mfma_f32_16x16x32_bf16 v[56:59], v[158:161], v[166:169], v[56:59]
	v_mfma_f32_16x16x32_bf16 v[52:55], v[150:153], v[174:177], v[52:55]
	v_mfma_f32_16x16x32_bf16 v[48:51], v[158:161], v[174:177], v[48:51]
	v_mfma_f32_16x16x32_bf16 v[36:39], v[150:153], v[182:185], v[36:39]
	v_mfma_f32_16x16x32_bf16 v[32:35], v[158:161], v[182:185], v[32:35]
	v_mfma_f32_16x16x32_bf16 v[20:23], v[150:153], v[190:193], v[20:23]
	v_mfma_f32_16x16x32_bf16 v[16:19], v[158:161], v[190:193], v[16:19]
	v_mfma_f32_16x16x32_bf16 v[60:63], v[154:157], v[170:173], v[60:63]
	v_mfma_f32_16x16x32_bf16 v[56:59], v[162:165], v[170:173], v[56:59]
	v_mfma_f32_16x16x32_bf16 v[52:55], v[154:157], v[178:181], v[52:55]
	v_mfma_f32_16x16x32_bf16 v[48:51], v[162:165], v[178:181], v[48:51]
	v_mfma_f32_16x16x32_bf16 v[36:39], v[154:157], v[186:189], v[36:39]
	v_mfma_f32_16x16x32_bf16 v[32:35], v[162:165], v[186:189], v[32:35]
	v_mfma_f32_16x16x32_bf16 v[20:23], v[154:157], v[194:197], v[20:23]
	v_mfma_f32_16x16x32_bf16 v[16:19], v[162:165], v[194:197], v[16:19]
	s_barrier
	s_add_u32 s30, s36, 0xa0000
	s_addc_u32 s31, s37, 0
	s_add_i32 s70, s55, s40
	v_lshl_add_u64 v[150:151], s[30:31], 0, v[130:131]
	s_mov_b32 m0, s70
	s_nop 0
	global_load_lds_dwordx4 v[150:151], off
	v_lshl_add_u64 v[150:151], s[30:31], 0, v[134:135]
	s_add_i32 m0, s70, 0x2000
	s_nop 0
	global_load_lds_dwordx4 v[150:151], off
	s_add_i32 s70, 0, 0x18000
	v_add_u32_e32 v162, s70, v146
	ds_read_b128 v[150:153], v162
	ds_read_b128 v[154:157], v162 offset:1024
	ds_read_b128 v[158:161], v162 offset:2048
	ds_read_b128 v[162:165], v162 offset:3072
	s_waitcnt vmcnt(6)
	s_barrier
	v_mfma_f32_16x16x32_bf16 v[44:47], v[198:201], v[166:169], v[44:47]
	v_mfma_f32_16x16x32_bf16 v[40:43], v[210:213], v[166:169], v[40:43]
	v_mfma_f32_16x16x32_bf16 v[28:31], v[198:201], v[174:177], v[28:31]
	v_mfma_f32_16x16x32_bf16 v[24:27], v[210:213], v[174:177], v[24:27]
	v_mfma_f32_16x16x32_bf16 v[12:15], v[198:201], v[182:185], v[12:15]
	v_mfma_f32_16x16x32_bf16 v[8:11], v[210:213], v[182:185], v[8:11]
	v_mfma_f32_16x16x32_bf16 v[4:7], v[198:201], v[190:193], v[4:7]
	v_mfma_f32_16x16x32_bf16 v[0:3], v[210:213], v[190:193], v[0:3]
	v_mfma_f32_16x16x32_bf16 v[44:47], v[202:205], v[170:173], v[44:47]
	v_mfma_f32_16x16x32_bf16 v[40:43], v[214:217], v[170:173], v[40:43]
	v_mfma_f32_16x16x32_bf16 v[28:31], v[202:205], v[178:181], v[28:31]
	v_mfma_f32_16x16x32_bf16 v[24:27], v[214:217], v[178:181], v[24:27]
	v_mfma_f32_16x16x32_bf16 v[12:15], v[202:205], v[186:189], v[12:15]
	v_mfma_f32_16x16x32_bf16 v[8:11], v[214:217], v[186:189], v[8:11]
	v_mfma_f32_16x16x32_bf16 v[4:7], v[202:205], v[194:197], v[4:7]
	v_mfma_f32_16x16x32_bf16 v[0:3], v[214:217], v[194:197], v[0:3]
	s_barrier
	s_add_u32 s30, s38, 0xa0000
	s_addc_u32 s31, s39, 0
	s_mov_b32 m0, s43
	v_lshl_add_u64 v[198:199], s[30:31], 0, v[128:129]
	ds_read_b128 v[166:169], v148 offset:32768
	ds_read_b128 v[170:173], v148 offset:33792
	ds_read_b128 v[174:177], v148 offset:34816
	ds_read_b128 v[178:181], v148 offset:35840
	ds_read_b128 v[182:185], v148 offset:36864
	ds_read_b128 v[186:189], v148 offset:37888
	ds_read_b128 v[190:193], v148 offset:38912
	ds_read_b128 v[194:197], v148 offset:39936
	global_load_lds_dwordx4 v[198:199], off
	v_lshl_add_u64 v[198:199], s[30:31], 0, v[132:133]
	s_mov_b32 m0, s44
	s_nop 0
	global_load_lds_dwordx4 v[198:199], off
	s_waitcnt lgkmcnt(8)
	s_barrier
	s_waitcnt lgkmcnt(0)
	s_waitcnt lgkmcnt(0)
	v_mfma_f32_16x16x32_bf16 v[124:127], v[150:153], v[166:169], v[124:127]
	v_mfma_f32_16x16x32_bf16 v[120:123], v[158:161], v[166:169], v[120:123]
	v_mfma_f32_16x16x32_bf16 v[116:119], v[150:153], v[174:177], v[116:119]
	v_mfma_f32_16x16x32_bf16 v[112:115], v[158:161], v[174:177], v[112:115]
	v_mfma_f32_16x16x32_bf16 v[100:103], v[150:153], v[182:185], v[100:103]
	v_mfma_f32_16x16x32_bf16 v[96:99], v[158:161], v[182:185], v[96:99]
	v_mfma_f32_16x16x32_bf16 v[84:87], v[150:153], v[190:193], v[84:87]
	v_mfma_f32_16x16x32_bf16 v[80:83], v[158:161], v[190:193], v[80:83]
	v_mfma_f32_16x16x32_bf16 v[124:127], v[154:157], v[170:173], v[124:127]
	v_mfma_f32_16x16x32_bf16 v[120:123], v[162:165], v[170:173], v[120:123]
	v_mfma_f32_16x16x32_bf16 v[116:119], v[154:157], v[178:181], v[116:119]
	v_mfma_f32_16x16x32_bf16 v[112:115], v[162:165], v[178:181], v[112:115]
	v_mfma_f32_16x16x32_bf16 v[100:103], v[154:157], v[186:189], v[100:103]
	v_mfma_f32_16x16x32_bf16 v[96:99], v[162:165], v[186:189], v[96:99]
	v_mfma_f32_16x16x32_bf16 v[84:87], v[154:157], v[194:197], v[84:87]
	v_mfma_f32_16x16x32_bf16 v[80:83], v[162:165], v[194:197], v[80:83]
	s_barrier
	s_add_i32 s38, 0, 0x1c000
	s_add_i32 s30, s70, s40
	v_add_u32_e32 v214, s38, v146
	v_lshl_add_u64 v[206:207], v[206:207], 0, s[14:15]
	s_mov_b32 m0, s30
	ds_read_b128 v[198:201], v214
	ds_read_b128 v[202:205], v214 offset:1024
	ds_read_b128 v[210:213], v214 offset:2048
	ds_read_b128 v[214:217], v214 offset:3072
	global_load_lds_dwordx4 v[206:207], off
	v_lshl_add_u64 v[206:207], v[218:219], 0, s[14:15]
	s_add_i32 m0, s30, 0x2000
	s_nop 0
	global_load_lds_dwordx4 v[206:207], off
	s_barrier
	s_waitcnt lgkmcnt(0)
	s_waitcnt lgkmcnt(0)
	v_mfma_f32_16x16x32_bf16 v[108:111], v[198:201], v[166:169], v[108:111]
	v_mfma_f32_16x16x32_bf16 v[104:107], v[210:213], v[166:169], v[104:107]
	v_mfma_f32_16x16x32_bf16 v[92:95], v[198:201], v[174:177], v[92:95]
	v_mfma_f32_16x16x32_bf16 v[88:91], v[210:213], v[174:177], v[88:91]
	v_mfma_f32_16x16x32_bf16 v[76:79], v[198:201], v[182:185], v[76:79]
	v_mfma_f32_16x16x32_bf16 v[72:75], v[210:213], v[182:185], v[72:75]
	v_mfma_f32_16x16x32_bf16 v[68:71], v[198:201], v[190:193], v[68:71]
	v_mfma_f32_16x16x32_bf16 v[64:67], v[210:213], v[190:193], v[64:67]
	v_mfma_f32_16x16x32_bf16 v[108:111], v[202:205], v[170:173], v[108:111]
	v_mfma_f32_16x16x32_bf16 v[104:107], v[214:217], v[170:173], v[104:107]
	v_mfma_f32_16x16x32_bf16 v[92:95], v[202:205], v[178:181], v[92:95]
	v_mfma_f32_16x16x32_bf16 v[88:91], v[214:217], v[178:181], v[88:91]
	v_mfma_f32_16x16x32_bf16 v[76:79], v[202:205], v[186:189], v[76:79]
	v_mfma_f32_16x16x32_bf16 v[72:75], v[214:217], v[186:189], v[72:75]
	v_mfma_f32_16x16x32_bf16 v[68:71], v[202:205], v[194:197], v[68:71]
	v_mfma_f32_16x16x32_bf16 v[64:67], v[214:217], v[194:197], v[64:67]
	s_mov_b32 m0, s52
	v_lshl_add_u64 v[206:207], v[220:221], 0, s[14:15]
	s_barrier
	ds_read_b128 v[166:169], v148 offset:49152
	ds_read_b128 v[170:173], v148 offset:50176
	ds_read_b128 v[174:177], v148 offset:51200
	ds_read_b128 v[178:181], v148 offset:52224
	ds_read_b128 v[182:185], v148 offset:53248
	ds_read_b128 v[186:189], v148 offset:54272
	ds_read_b128 v[190:193], v148 offset:55296
	ds_read_b128 v[194:197], v148 offset:56320
	global_load_lds_dwordx4 v[206:207], off
	v_lshl_add_u64 v[206:207], v[222:223], 0, s[14:15]
	s_mov_b32 m0, s53
	s_nop 0
	global_load_lds_dwordx4 v[206:207], off
	s_waitcnt vmcnt(10)
	s_barrier
	s_waitcnt lgkmcnt(0)
	s_waitcnt lgkmcnt(0)
	v_mfma_f32_16x16x32_bf16 v[60:63], v[150:153], v[166:169], v[60:63]
	v_mfma_f32_16x16x32_bf16 v[56:59], v[158:161], v[166:169], v[56:59]
	v_mfma_f32_16x16x32_bf16 v[52:55], v[150:153], v[174:177], v[52:55]
	v_mfma_f32_16x16x32_bf16 v[48:51], v[158:161], v[174:177], v[48:51]
	v_mfma_f32_16x16x32_bf16 v[36:39], v[150:153], v[182:185], v[36:39]
	v_mfma_f32_16x16x32_bf16 v[32:35], v[158:161], v[182:185], v[32:35]
	v_mfma_f32_16x16x32_bf16 v[20:23], v[150:153], v[190:193], v[20:23]
	v_mfma_f32_16x16x32_bf16 v[16:19], v[158:161], v[190:193], v[16:19]
	v_mfma_f32_16x16x32_bf16 v[60:63], v[154:157], v[170:173], v[60:63]
	v_mfma_f32_16x16x32_bf16 v[56:59], v[162:165], v[170:173], v[56:59]
	v_mfma_f32_16x16x32_bf16 v[52:55], v[154:157], v[178:181], v[52:55]
	v_mfma_f32_16x16x32_bf16 v[48:51], v[162:165], v[178:181], v[48:51]
	v_mfma_f32_16x16x32_bf16 v[36:39], v[154:157], v[186:189], v[36:39]
	v_mfma_f32_16x16x32_bf16 v[32:35], v[162:165], v[186:189], v[32:35]
	v_mfma_f32_16x16x32_bf16 v[20:23], v[154:157], v[194:197], v[20:23]
	v_mfma_f32_16x16x32_bf16 v[16:19], v[162:165], v[194:197], v[16:19]
	s_barrier
	s_add_u32 s30, s36, 0xa0080
	s_addc_u32 s31, s37, 0
	s_add_i32 s36, s38, s40
	v_lshl_add_u64 v[150:151], s[30:31], 0, v[130:131]
	s_mov_b32 m0, s36
	s_nop 0
	global_load_lds_dwordx4 v[150:151], off
	v_lshl_add_u64 v[150:151], s[30:31], 0, v[134:135]
	s_add_i32 m0, s36, 0x2000
	s_nop 0
	global_load_lds_dwordx4 v[150:151], off
	ds_read_b128 v[150:153], v147
	ds_read_b128 v[154:157], v147 offset:1024
	ds_read_b128 v[158:161], v147 offset:2048
	ds_read_b128 v[162:165], v147 offset:3072
	s_waitcnt vmcnt(6)
	s_barrier
	s_waitcnt lgkmcnt(0)
	v_mfma_f32_16x16x32_bf16 v[44:47], v[198:201], v[166:169], v[44:47]
	v_mfma_f32_16x16x32_bf16 v[40:43], v[210:213], v[166:169], v[40:43]
	v_mfma_f32_16x16x32_bf16 v[28:31], v[198:201], v[174:177], v[28:31]
	v_mfma_f32_16x16x32_bf16 v[24:27], v[210:213], v[174:177], v[24:27]
	v_mfma_f32_16x16x32_bf16 v[12:15], v[198:201], v[182:185], v[12:15]
	v_mfma_f32_16x16x32_bf16 v[8:11], v[210:213], v[182:185], v[8:11]
	v_mfma_f32_16x16x32_bf16 v[4:7], v[198:201], v[190:193], v[4:7]
	v_mfma_f32_16x16x32_bf16 v[0:3], v[210:213], v[190:193], v[0:3]
	v_mfma_f32_16x16x32_bf16 v[44:47], v[202:205], v[170:173], v[44:47]
	v_mfma_f32_16x16x32_bf16 v[40:43], v[214:217], v[170:173], v[40:43]
	v_mfma_f32_16x16x32_bf16 v[28:31], v[202:205], v[178:181], v[28:31]
	v_mfma_f32_16x16x32_bf16 v[24:27], v[214:217], v[178:181], v[24:27]
	v_mfma_f32_16x16x32_bf16 v[12:15], v[202:205], v[186:189], v[12:15]
	v_mfma_f32_16x16x32_bf16 v[8:11], v[214:217], v[186:189], v[8:11]
	v_mfma_f32_16x16x32_bf16 v[4:7], v[202:205], v[194:197], v[4:7]
	v_mfma_f32_16x16x32_bf16 v[0:3], v[214:217], v[194:197], v[0:3]
	s_add_i32 s69, s69, 2
	s_add_u32 s67, s67, 0x100
	s_addc_u32 s68, s68, 0
	s_cmp_gt_u32 s69, 37
	s_mov_b64 s[30:31], s[34:35]
	s_barrier
	s_cbranch_scc0 .LBB0_1402
	v_mov_b32_e32 v150, v145
	v_mov_b32_e32 v151, v144
	s_lshl_b32 s30, s63, 8
	s_add_i32 s30, s30, s49
	v_add_u32_e32 v150, s30, v150
	s_lshl_b32 s30, s66, 8
	s_or_b32 s30, s30, s51
	v_lshl_add_u32 v152, v151, 3, s30
	v_ashrrev_i32_e32 v151, 31, v150
	v_lshlrev_b64 v[150:151], 12, v[150:151]
	v_ashrrev_i32_e32 v153, 31, v152
	v_lshl_add_u64 v[150:151], s[10:11], 0, v[150:151]
	v_lshl_add_u64 v[150:151], v[152:153], 1, v[150:151]
	v_cvt_pk_bf16_f32 v108, v108, v109
	v_cvt_pk_bf16_f32 v109, v110, v111
	v_cvt_pk_bf16_f32 v110, v104, v105
	v_cvt_pk_bf16_f32 v111, v106, v107
	global_store_dwordx4 v[150:151], v[108:111], off offset:256
	v_cvt_pk_bf16_f32 v92, v92, v93
	v_cvt_pk_bf16_f32 v93, v94, v95
	v_add_co_u32_e32 v110, vcc, s48, v150
	v_lshl_add_u64 v[108:109], v[150:151], 0, s[18:19]
	s_nop 0
	v_addc_co_u32_e32 v111, vcc, 0, v151, vcc
	v_cvt_pk_bf16_f32 v94, v88, v89
	v_cvt_pk_bf16_f32 v95, v90, v91
	global_store_dwordx4 v[108:109], v[92:95], off offset:256
	v_cvt_pk_bf16_f32 v76, v76, v77
	v_cvt_pk_bf16_f32 v77, v78, v79
	v_add_co_u32_e32 v94, vcc, s56, v150
	v_lshl_add_u64 v[92:93], v[150:151], 0, s[20:21]
	s_nop 0
	v_addc_co_u32_e32 v95, vcc, 0, v151, vcc
	v_cvt_pk_bf16_f32 v78, v72, v73
	v_cvt_pk_bf16_f32 v79, v74, v75
	global_store_dwordx4 v[92:93], v[76:79], off offset:256
	v_cvt_pk_bf16_f32 v60, v60, v61
	v_cvt_pk_bf16_f32 v61, v62, v63
	v_add_co_u32_e32 v78, vcc, s57, v150
	v_cvt_pk_bf16_f32 v62, v56, v57
	s_nop 0
	v_addc_co_u32_e32 v79, vcc, 0, v151, vcc
	v_add_co_u32_e32 v56, vcc, s59, v150
	v_cvt_pk_bf16_f32 v68, v68, v69
	v_cvt_pk_bf16_f32 v69, v70, v71
	v_cvt_pk_bf16_f32 v70, v64, v65
	v_lshl_add_u64 v[64:65], v[150:151], 0, s[24:25]
	v_addc_co_u32_e32 v57, vcc, 0, v151, vcc
	v_cvt_pk_bf16_f32 v44, v44, v45
	v_cvt_pk_bf16_f32 v45, v46, v47
	v_cvt_pk_bf16_f32 v46, v40, v41
	v_cvt_pk_bf16_f32 v47, v42, v43
	global_store_dwordx4 v[64:65], v[44:47], off offset:256
	v_cvt_pk_bf16_f32 v28, v28, v29
	v_cvt_pk_bf16_f32 v29, v30, v31
	v_add_co_u32_e32 v46, vcc, s60, v150
	v_lshl_add_u64 v[44:45], v[150:151], 0, s[26:27]
	s_nop 0
	v_addc_co_u32_e32 v47, vcc, 0, v151, vcc
	v_cvt_pk_bf16_f32 v30, v24, v25
	v_cvt_pk_bf16_f32 v31, v26, v27
	global_store_dwordx4 v[44:45], v[28:31], off offset:256
	v_cvt_pk_bf16_f32 v12, v12, v13
	v_cvt_pk_bf16_f32 v13, v14, v15
	v_add_co_u32_e32 v30, vcc, s61, v150
	v_lshl_add_u64 v[28:29], v[150:151], 0, s[8:9]
	s_nop 0
	v_addc_co_u32_e32 v31, vcc, 0, v151, vcc
	v_cvt_pk_bf16_f32 v14, v8, v9
	v_cvt_pk_bf16_f32 v15, v10, v11
	global_store_dwordx4 v[28:29], v[12:15], off offset:256
	v_cvt_pk_bf16_f32 v124, v124, v125
	v_cvt_pk_bf16_f32 v125, v126, v127
	v_add_co_u32_e32 v14, vcc, s62, v150
	v_cvt_pk_bf16_f32 v126, v120, v121
	s_nop 0
	v_addc_co_u32_e32 v15, vcc, 0, v151, vcc
	v_cvt_pk_bf16_f32 v127, v122, v123
	v_cvt_pk_bf16_f32 v104, v116, v117
	v_cvt_pk_bf16_f32 v105, v118, v119
	v_cvt_pk_bf16_f32 v106, v112, v113
	v_cvt_pk_bf16_f32 v107, v114, v115
	v_cvt_pk_bf16_f32 v88, v100, v101
	v_cvt_pk_bf16_f32 v89, v102, v103
	v_cvt_pk_bf16_f32 v90, v96, v97
	v_cvt_pk_bf16_f32 v91, v98, v99
	v_lshl_add_u64 v[76:77], v[150:151], 0, s[22:23]
	v_cvt_pk_bf16_f32 v72, v84, v85
	v_cvt_pk_bf16_f32 v73, v86, v87
	v_cvt_pk_bf16_f32 v74, v80, v81
	v_cvt_pk_bf16_f32 v75, v82, v83
	v_cvt_pk_bf16_f32 v71, v66, v67
	v_cvt_pk_bf16_f32 v63, v58, v59
	v_cvt_pk_bf16_f32 v40, v52, v53
	v_cvt_pk_bf16_f32 v41, v54, v55
	v_cvt_pk_bf16_f32 v42, v48, v49
	v_cvt_pk_bf16_f32 v43, v50, v51
	v_cvt_pk_bf16_f32 v24, v36, v37
	v_cvt_pk_bf16_f32 v25, v38, v39
	v_cvt_pk_bf16_f32 v26, v32, v33
	v_cvt_pk_bf16_f32 v27, v34, v35
	v_lshl_add_u64 v[12:13], v[150:151], 0, s[28:29]
	v_cvt_pk_bf16_f32 v8, v20, v21
	v_cvt_pk_bf16_f32 v9, v22, v23
	v_cvt_pk_bf16_f32 v10, v16, v17
	v_cvt_pk_bf16_f32 v11, v18, v19
	v_cvt_pk_bf16_f32 v4, v4, v5
	v_cvt_pk_bf16_f32 v5, v6, v7
	v_cvt_pk_bf16_f32 v6, v0, v1
	v_cvt_pk_bf16_f32 v7, v2, v3
	s_and_b64 vcc, exec, s[2:3]
	s_mov_b32 s66, s64
	s_mov_b32 s63, s65
	s_mov_b64 s[34:35], s[6:7]
	s_mov_b64 s[30:31], s[4:5]
	global_store_dwordx4 v[150:151], v[124:127], off
	global_store_dwordx4 v[110:111], v[104:107], off
	global_store_dwordx4 v[94:95], v[88:91], off
	global_store_dwordx4 v[78:79], v[72:75], off
	global_store_dwordx4 v[76:77], v[68:71], off offset:256
	global_store_dwordx4 v[56:57], v[60:63], off
	global_store_dwordx4 v[46:47], v[40:43], off
	global_store_dwordx4 v[30:31], v[24:27], off
	global_store_dwordx4 v[14:15], v[8:11], off
	global_store_dwordx4 v[12:13], v[4:7], off offset:256
	s_cbranch_vccz .LBB0_1391
	s_waitcnt vmcnt(0)
	s_cmpk_gt_u32 s33, 0xff
	s_cbranch_scc1 .LBB0_1406
	s_barrier
